# v041 stack + K-loop hand-off trim: s_setprio moved off the MFMA-to-MFMA hand-off path, redundant lgkmcnt(0) after barrier deleted (20 sites)
# baseline (speedup 1.0000x reference)
; #define PG8_STAGE(bufoff, gbase, voff) do { _Pragma("unroll") for (int _i = 0; _i < 2; ++_i) \
;         __builtin_amdgcn_global_load_lds((const unsigned*)((const char*)(gbase) + (voff)[_i]), (PG8_LAS unsigned*)(lds + (bufoff) + ldsw + _i * 8192), 16, 0, 0); } while (0)
; #define PG8_LDA(dst, b, h) do { _Pragma("unroll") for (int m = 0; m < 4; ++m) _Pragma("unroll") for (int k = 0; k < 2; ++k) dst[m][k] = *(const PG8_LAS bf16x8*)(lds + PG8_SA(b, h) + aoff + m * 2048 + k * 1024); } while (0)
; #define PG8_LDB(dst, b, h) do { _Pragma("unroll") for (int n = 0; n < 2; ++n) _Pragma("unroll") for (int k = 0; k < 2; ++k) dst[n][k] = *(const PG8_LAS bf16x8*)(lds + PG8_SB(b, h) + boff + n * 2048 + k * 1024); } while (0)
; #define PG8_MMA(ai, bj, At, Bt) do { __builtin_amdgcn_s_setprio(1); _Pragma("unroll") for (int m = 0; m < 4; ++m) _Pragma("unroll") for (int n = 0; n < 2; ++n) _Pragma("unroll") for (int k = 0; k < 2; ++k) \
;         acc[ai][bj][m][n] = __builtin_amdgcn_mfma_f32_16x16x32_bf16(Bt[n][k], At[m][k], acc[ai][bj][m][n], 0, 0, 0); __builtin_amdgcn_s_setprio(0); } while (0)
; #define PG8_WAIT_V(n) asm volatile("s_waitcnt vmcnt(" #n ")" ::: "memory")
; #define PG8_WAIT_L(n) asm volatile("s_waitcnt lgkmcnt(" #n ")" ::: "memory")
; #define PG8_BAR __builtin_amdgcn_s_barrier()
; #define PG8_SCHED __builtin_amdgcn_sched_barrier(0)
; template <class Epi, class Sched, bool ALIGN_EPI = false, bool SP2 = false>
; __device__ __forceinline__ void gemm_phase(PG8_LAS unsigned char* lds, const Gemm g, const Sched& S, const Epi& E, const int tid) {
;     ...
;             PG8_LDB(B0, 0, 0); PG8_LDB(B1, 0, 1); PG8_SCHED; PG8_LDA(At, 0, 0); PG8_STAGE(PG8_SA(1, 1), a1 + hstep, voffA);
;             PG8_WAIT_V(8); PG8_WAIT_L(0); PG8_BAR; PG8_MMA(0, 0, At, B0); PG8_MMA(0, 1, At, B1); PG8_BAR; PG8_SCHED;
;             PG8_LDA(At, 0, 1); PG8_STAGE(PG8_SB(0, 0), b2, voffB); PG8_STAGE(PG8_SB(0, 1), b2 + hstep, voffB); PG8_STAGE(PG8_SA(0, 0), a2, voffA);
;             PG8_WAIT_V(8); PG8_WAIT_L(0); PG8_BAR; PG8_MMA(1, 0, At, B0); PG8_MMA(1, 1, At, B1); PG8_BAR; PG8_SCHED;
.LBB0_35:
	s_add_u32 s34, s18, 0xfffc0080
	s_addc_u32 s35, s19, -1
	s_add_i32 s86, 0, 0x10000
	s_cmp_eq_u32 s85, 12
	s_cselect_b32 s65, s46, s35
	s_cselect_b32 s64, s47, s34
	s_cselect_b32 s35, s57, s84
	s_cselect_b32 s34, s59, s24
	s_add_i32 s88, 0, 0x14000
	v_add_u32_e32 v96, s86, v243
	v_add_u32_e32 v112, s88, v243
	ds_read_b128 v[84:87], v96
	ds_read_b128 v[88:91], v96 offset:1024
	ds_read_b128 v[92:95], v96 offset:2048
	ds_read_b128 v[96:99], v96 offset:3072
	ds_read_b128 v[100:103], v112
	ds_read_b128 v[104:107], v112 offset:1024
	ds_read_b128 v[108:111], v112 offset:2048
	ds_read_b128 v[112:115], v112 offset:3072
	v_lshl_add_u64 v[214:215], s[18:19], 0, v[172:173]
	s_add_i32 m0, s29, 0xc000
	ds_read_b128 v[176:179], v245
	ds_read_b128 v[180:183], v245 offset:1024
	ds_read_b128 v[184:187], v245 offset:2048
	ds_read_b128 v[188:191], v245 offset:3072
	ds_read_b128 v[192:195], v245 offset:4096
	ds_read_b128 v[202:205], v245 offset:5120
	ds_read_b128 v[206:209], v245 offset:6144
	ds_read_b128 v[210:213], v245 offset:7168
	global_load_lds_dwordx4 v[214:215], off
	v_lshl_add_u64 v[214:215], s[18:19], 0, v[174:175]
	s_add_i32 m0, s29, 0xe000
	s_nop 0
	global_load_lds_dwordx4 v[214:215], off
	s_waitcnt vmcnt(8)
	s_waitcnt lgkmcnt(0)
	s_setprio 1
	s_barrier
	v_mfma_f32_16x16x32_bf16 v[160:163], v[84:87], v[176:179], v[160:163]
	v_mfma_f32_16x16x32_bf16 v[156:159], v[92:95], v[176:179], v[156:159]
	v_mfma_f32_16x16x32_bf16 v[64:67], v[84:87], v[184:187], v[64:67]
	v_mfma_f32_16x16x32_bf16 v[60:63], v[92:95], v[184:187], v[60:63]
	v_mfma_f32_16x16x32_bf16 v[52:55], v[84:87], v[192:195], v[52:55]
	v_mfma_f32_16x16x32_bf16 v[48:51], v[92:95], v[192:195], v[48:51]
	v_mfma_f32_16x16x32_bf16 v[148:151], v[84:87], v[206:209], v[148:151]
	v_mfma_f32_16x16x32_bf16 v[144:147], v[92:95], v[206:209], v[144:147]
	v_mfma_f32_16x16x32_bf16 v[160:163], v[88:91], v[180:183], v[160:163]
	v_mfma_f32_16x16x32_bf16 v[156:159], v[96:99], v[180:183], v[156:159]
	v_mfma_f32_16x16x32_bf16 v[64:67], v[88:91], v[188:191], v[64:67]
	v_mfma_f32_16x16x32_bf16 v[60:63], v[96:99], v[188:191], v[60:63]
	v_mfma_f32_16x16x32_bf16 v[52:55], v[88:91], v[202:205], v[52:55]
	v_mfma_f32_16x16x32_bf16 v[48:51], v[96:99], v[202:205], v[48:51]
	v_mfma_f32_16x16x32_bf16 v[148:151], v[88:91], v[210:213], v[148:151]
	v_mfma_f32_16x16x32_bf16 v[144:147], v[96:99], v[210:213], v[144:147]
	s_setprio 0
	s_setprio 1
	v_mfma_f32_16x16x32_bf16 v[152:155], v[100:103], v[176:179], v[152:155]
	v_mfma_f32_16x16x32_bf16 v[140:143], v[108:111], v[176:179], v[140:143]
	v_mfma_f32_16x16x32_bf16 v[56:59], v[100:103], v[184:187], v[56:59]
	v_mfma_f32_16x16x32_bf16 v[44:47], v[108:111], v[184:187], v[44:47]
	v_mfma_f32_16x16x32_bf16 v[40:43], v[100:103], v[192:195], v[40:43]
	v_mfma_f32_16x16x32_bf16 v[36:39], v[108:111], v[192:195], v[36:39]
	v_mfma_f32_16x16x32_bf16 v[136:139], v[100:103], v[206:209], v[136:139]
	v_mfma_f32_16x16x32_bf16 v[132:135], v[108:111], v[206:209], v[132:135]
	v_mfma_f32_16x16x32_bf16 v[152:155], v[104:107], v[180:183], v[152:155]
	v_mfma_f32_16x16x32_bf16 v[140:143], v[112:115], v[180:183], v[140:143]
	v_mfma_f32_16x16x32_bf16 v[56:59], v[104:107], v[188:191], v[56:59]
	v_mfma_f32_16x16x32_bf16 v[44:47], v[112:115], v[188:191], v[44:47]
	v_mfma_f32_16x16x32_bf16 v[40:43], v[104:107], v[202:205], v[40:43]
	v_mfma_f32_16x16x32_bf16 v[36:39], v[112:115], v[202:205], v[36:39]
	v_mfma_f32_16x16x32_bf16 v[136:139], v[104:107], v[210:213], v[136:139]
	v_mfma_f32_16x16x32_bf16 v[132:135], v[112:115], v[210:213], v[132:135]
	s_barrier
	s_setprio 0
	s_add_i32 s86, s86, s2
	v_lshl_add_u64 v[218:219], s[34:35], 0, v[166:167]
	s_mov_b32 m0, s86
	ds_read_b128 v[176:179], v245 offset:16384
	ds_read_b128 v[180:183], v245 offset:17408
	ds_read_b128 v[184:187], v245 offset:18432
	ds_read_b128 v[188:191], v245 offset:19456
	ds_read_b128 v[192:195], v245 offset:20480
	ds_read_b128 v[202:205], v245 offset:21504
	ds_read_b128 v[206:209], v245 offset:22528
	ds_read_b128 v[210:213], v245 offset:23552
	global_load_lds_dwordx4 v[218:219], off
	s_add_i32 m0, s86, 0x2000
	s_add_u32 s86, s34, 0x40000
	v_lshl_add_u64 v[220:221], s[34:35], 0, v[0:1]
	s_addc_u32 s87, s35, 0
	s_add_i32 s88, s88, s2
	global_load_lds_dwordx4 v[220:221], off
	v_lshl_add_u64 v[214:215], s[86:87], 0, v[166:167]
	s_mov_b32 m0, s88
	v_lshl_add_u64 v[222:223], s[64:65], 0, v[168:169]
	global_load_lds_dwordx4 v[214:215], off
	v_lshl_add_u64 v[214:215], s[86:87], 0, v[0:1]
	s_add_i32 m0, s88, 0x2000
	v_lshl_add_u64 v[224:225], s[64:65], 0, v[164:165]
	global_load_lds_dwordx4 v[214:215], off
	s_mov_b32 m0, s29
	s_nop 0
	global_load_lds_dwordx4 v[222:223], off
	s_mov_b32 m0, s45
	s_nop 0
	global_load_lds_dwordx4 v[224:225], off
	s_waitcnt vmcnt(8)
	s_waitcnt lgkmcnt(0)
	s_setprio 1
	s_barrier
; #define PG8_STAGE(bufoff, gbase, voff) do { _Pragma("unroll") for (int _i = 0; _i < 2; ++_i) \
;         __builtin_amdgcn_global_load_lds((const unsigned*)((const char*)(gbase) + (voff)[_i]), (PG8_LAS unsigned*)(lds + (bufoff) + ldsw + _i * 8192), 16, 0, 0); } while (0)
; #define PG8_LDA(dst, b, h) do { _Pragma("unroll") for (int m = 0; m < 4; ++m) _Pragma("unroll") for (int k = 0; k < 2; ++k) dst[m][k] = *(const PG8_LAS bf16x8*)(lds + PG8_SA(b, h) + aoff + m * 2048 + k * 1024); } while (0)
; #define PG8_LDB(dst, b, h) do { _Pragma("unroll") for (int n = 0; n < 2; ++n) _Pragma("unroll") for (int k = 0; k < 2; ++k) dst[n][k] = *(const PG8_LAS bf16x8*)(lds + PG8_SB(b, h) + boff + n * 2048 + k * 1024); } while (0)
; #define PG8_MMA(ai, bj, At, Bt) do { __builtin_amdgcn_s_setprio(1); _Pragma("unroll") for (int m = 0; m < 4; ++m) _Pragma("unroll") for (int n = 0; n < 2; ++n) _Pragma("unroll") for (int k = 0; k < 2; ++k) \
;         acc[ai][bj][m][n] = __builtin_amdgcn_mfma_f32_16x16x32_bf16(Bt[n][k], At[m][k], acc[ai][bj][m][n], 0, 0, 0); __builtin_amdgcn_s_setprio(0); } while (0)
; #define PG8_WAIT_V(n) asm volatile("s_waitcnt vmcnt(" #n ")" ::: "memory")
; #define PG8_WAIT_L(n) asm volatile("s_waitcnt lgkmcnt(" #n ")" ::: "memory")
; #define PG8_BAR __builtin_amdgcn_s_barrier()
; #define PG8_SCHED __builtin_amdgcn_sched_barrier(0)
; template <class Epi, class Sched, bool ALIGN_EPI = false, bool SP2 = false>
; __device__ __forceinline__ void gemm_phase(PG8_LAS unsigned char* lds, const Gemm g, const Sched& S, const Epi& E, const int tid) {
;     ...
;             PG8_LDA(At, 0, 1); PG8_STAGE(PG8_SB(0, 0), b2, voffB); PG8_STAGE(PG8_SB(0, 1), b2 + hstep, voffB); PG8_STAGE(PG8_SA(0, 0), a2, voffA);
;             PG8_WAIT_V(8); PG8_WAIT_L(0); PG8_BAR; PG8_MMA(1, 0, At, B0); PG8_MMA(1, 1, At, B1); PG8_BAR; PG8_SCHED;
;             PG8_LDB(B0, 1, 0); PG8_LDB(B1, 1, 1); PG8_SCHED; PG8_LDA(At, 1, 0); PG8_STAGE(PG8_SA(0, 1), a2 + hstep, voffA);
;             PG8_WAIT_V(8); PG8_WAIT_L(0); PG8_BAR; PG8_MMA(0, 0, At, B0); PG8_MMA(0, 1, At, B1); PG8_BAR; PG8_SCHED;
	v_mfma_f32_16x16x32_bf16 v[128:131], v[84:87], v[176:179], v[128:131]
	v_mfma_f32_16x16x32_bf16 v[116:119], v[92:95], v[176:179], v[116:119]
	v_mfma_f32_16x16x32_bf16 v[32:35], v[84:87], v[184:187], v[32:35]
	v_mfma_f32_16x16x32_bf16 v[28:31], v[92:95], v[184:187], v[28:31]
	v_mfma_f32_16x16x32_bf16 v[20:23], v[84:87], v[192:195], v[20:23]
	v_mfma_f32_16x16x32_bf16 v[16:19], v[92:95], v[192:195], v[16:19]
	v_mfma_f32_16x16x32_bf16 v[80:83], v[84:87], v[206:209], v[80:83]
	v_mfma_f32_16x16x32_bf16 v[72:75], v[92:95], v[206:209], v[72:75]
	v_mfma_f32_16x16x32_bf16 v[128:131], v[88:91], v[180:183], v[128:131]
	v_mfma_f32_16x16x32_bf16 v[116:119], v[96:99], v[180:183], v[116:119]
	v_mfma_f32_16x16x32_bf16 v[32:35], v[88:91], v[188:191], v[32:35]
	v_mfma_f32_16x16x32_bf16 v[28:31], v[96:99], v[188:191], v[28:31]
	v_mfma_f32_16x16x32_bf16 v[20:23], v[88:91], v[202:205], v[20:23]
	v_mfma_f32_16x16x32_bf16 v[16:19], v[96:99], v[202:205], v[16:19]
	v_mfma_f32_16x16x32_bf16 v[80:83], v[88:91], v[210:213], v[80:83]
	v_mfma_f32_16x16x32_bf16 v[72:75], v[96:99], v[210:213], v[72:75]
	s_setprio 0
	s_setprio 1
	v_mfma_f32_16x16x32_bf16 v[24:27], v[100:103], v[184:187], v[24:27]
	v_mfma_f32_16x16x32_bf16 v[12:15], v[108:111], v[184:187], v[12:15]
	v_mfma_f32_16x16x32_bf16 v[8:11], v[100:103], v[192:195], v[8:11]
	v_mfma_f32_16x16x32_bf16 v[4:7], v[108:111], v[192:195], v[4:7]
	v_mfma_f32_16x16x32_bf16 v[76:79], v[100:103], v[206:209], v[76:79]
	v_mfma_f32_16x16x32_bf16 v[68:71], v[108:111], v[206:209], v[68:71]
	v_mfma_f32_16x16x32_bf16 v[84:87], v[100:103], v[176:179], v[124:127]
	v_mfma_f32_16x16x32_bf16 v[88:91], v[108:111], v[176:179], v[120:123]
	v_mfma_f32_16x16x32_bf16 v[24:27], v[104:107], v[188:191], v[24:27]
	v_mfma_f32_16x16x32_bf16 v[12:15], v[112:115], v[188:191], v[12:15]
	v_mfma_f32_16x16x32_bf16 v[8:11], v[104:107], v[202:205], v[8:11]
	v_mfma_f32_16x16x32_bf16 v[4:7], v[112:115], v[202:205], v[4:7]
	v_mfma_f32_16x16x32_bf16 v[76:79], v[104:107], v[210:213], v[76:79]
	v_mfma_f32_16x16x32_bf16 v[68:71], v[112:115], v[210:213], v[68:71]
	v_mfma_f32_16x16x32_bf16 v[84:87], v[104:107], v[180:183], v[84:87]
	v_mfma_f32_16x16x32_bf16 v[88:91], v[112:115], v[180:183], v[88:91]
	s_barrier
	s_setprio 0
	s_add_i32 s86, 0, 0x18000
	s_add_i32 s87, 0, 0x1c000
	v_add_u32_e32 v104, s86, v243
	v_add_u32_e32 v120, s87, v243
	ds_read_b128 v[92:95], v104
	ds_read_b128 v[96:99], v104 offset:1024
	ds_read_b128 v[100:103], v104 offset:2048
	ds_read_b128 v[104:107], v104 offset:3072
	ds_read_b128 v[108:111], v120
	ds_read_b128 v[112:115], v120 offset:1024
	ds_read_b128 v[176:179], v120 offset:2048
	ds_read_b128 v[180:183], v120 offset:3072
	s_add_u32 s64, s64, 0x40000
	s_addc_u32 s65, s65, 0
	s_mov_b32 m0, s3
	v_lshl_add_u64 v[214:215], s[64:65], 0, v[168:169]
	ds_read_b128 v[120:123], v245 offset:32768
	ds_read_b128 v[124:127], v245 offset:33792
	ds_read_b128 v[184:187], v245 offset:34816
	ds_read_b128 v[188:191], v245 offset:35840
	ds_read_b128 v[192:195], v245 offset:36864
	ds_read_b128 v[202:205], v245 offset:37888
	ds_read_b128 v[206:209], v245 offset:38912
	ds_read_b128 v[210:213], v245 offset:39936
	global_load_lds_dwordx4 v[214:215], off
	v_lshl_add_u64 v[214:215], s[64:65], 0, v[164:165]
	s_mov_b32 m0, s50
	s_nop 0
	global_load_lds_dwordx4 v[214:215], off
	s_waitcnt vmcnt(8)
	s_waitcnt lgkmcnt(0)
	s_setprio 1
	s_barrier
	v_mfma_f32_16x16x32_bf16 v[160:163], v[92:95], v[120:123], v[160:163]
	v_mfma_f32_16x16x32_bf16 v[156:159], v[100:103], v[120:123], v[156:159]
	v_mfma_f32_16x16x32_bf16 v[64:67], v[92:95], v[184:187], v[64:67]
	v_mfma_f32_16x16x32_bf16 v[60:63], v[100:103], v[184:187], v[60:63]
	v_mfma_f32_16x16x32_bf16 v[52:55], v[92:95], v[192:195], v[52:55]
	v_mfma_f32_16x16x32_bf16 v[48:51], v[100:103], v[192:195], v[48:51]
	v_mfma_f32_16x16x32_bf16 v[148:151], v[92:95], v[206:209], v[148:151]
	v_mfma_f32_16x16x32_bf16 v[144:147], v[100:103], v[206:209], v[144:147]
	v_mfma_f32_16x16x32_bf16 v[160:163], v[96:99], v[124:127], v[160:163]
	v_mfma_f32_16x16x32_bf16 v[156:159], v[104:107], v[124:127], v[156:159]
	v_mfma_f32_16x16x32_bf16 v[64:67], v[96:99], v[188:191], v[64:67]
	v_mfma_f32_16x16x32_bf16 v[60:63], v[104:107], v[188:191], v[60:63]
	v_mfma_f32_16x16x32_bf16 v[52:55], v[96:99], v[202:205], v[52:55]
	v_mfma_f32_16x16x32_bf16 v[48:51], v[104:107], v[202:205], v[48:51]
	v_mfma_f32_16x16x32_bf16 v[148:151], v[96:99], v[210:213], v[148:151]
	v_mfma_f32_16x16x32_bf16 v[144:147], v[104:107], v[210:213], v[144:147]
	s_setprio 0
	s_setprio 1
	v_mfma_f32_16x16x32_bf16 v[152:155], v[108:111], v[120:123], v[152:155]
	v_mfma_f32_16x16x32_bf16 v[120:123], v[176:179], v[120:123], v[140:143]
	v_mfma_f32_16x16x32_bf16 v[140:143], v[180:183], v[124:127], v[120:123]
	v_mfma_f32_16x16x32_bf16 v[120:123], v[108:111], v[206:209], v[136:139]
	v_mfma_f32_16x16x32_bf16 v[56:59], v[108:111], v[184:187], v[56:59]
	v_mfma_f32_16x16x32_bf16 v[44:47], v[176:179], v[184:187], v[44:47]
	v_mfma_f32_16x16x32_bf16 v[40:43], v[108:111], v[192:195], v[40:43]
	v_mfma_f32_16x16x32_bf16 v[36:39], v[176:179], v[192:195], v[36:39]
	v_mfma_f32_16x16x32_bf16 v[136:139], v[112:115], v[210:213], v[120:123]
	v_mfma_f32_16x16x32_bf16 v[120:123], v[176:179], v[206:209], v[132:135]
	v_mfma_f32_16x16x32_bf16 v[152:155], v[112:115], v[124:127], v[152:155]
	v_mfma_f32_16x16x32_bf16 v[56:59], v[112:115], v[188:191], v[56:59]
	v_mfma_f32_16x16x32_bf16 v[44:47], v[180:183], v[188:191], v[44:47]
	v_mfma_f32_16x16x32_bf16 v[40:43], v[112:115], v[202:205], v[40:43]
	v_mfma_f32_16x16x32_bf16 v[36:39], v[180:183], v[202:205], v[36:39]
	v_mfma_f32_16x16x32_bf16 v[132:135], v[180:183], v[210:213], v[120:123]
	s_barrier
; #define PG8_STAGE(bufoff, gbase, voff) do { _Pragma("unroll") for (int _i = 0; _i < 2; ++_i) \
;         __builtin_amdgcn_global_load_lds((const unsigned*)((const char*)(gbase) + (voff)[_i]), (PG8_LAS unsigned*)(lds + (bufoff) + ldsw + _i * 8192), 16, 0, 0); } while (0)
; #define PG8_LDA(dst, b, h) do { _Pragma("unroll") for (int m = 0; m < 4; ++m) _Pragma("unroll") for (int k = 0; k < 2; ++k) dst[m][k] = *(const PG8_LAS bf16x8*)(lds + PG8_SA(b, h) + aoff + m * 2048 + k * 1024); } while (0)
; #define PG8_MMA(ai, bj, At, Bt) do { __builtin_amdgcn_s_setprio(1); _Pragma("unroll") for (int m = 0; m < 4; ++m) _Pragma("unroll") for (int n = 0; n < 2; ++n) _Pragma("unroll") for (int k = 0; k < 2; ++k) \
;         acc[ai][bj][m][n] = __builtin_amdgcn_mfma_f32_16x16x32_bf16(Bt[n][k], At[m][k], acc[ai][bj][m][n], 0, 0, 0); __builtin_amdgcn_s_setprio(0); } while (0)
; #define PG8_WAIT_V(n) asm volatile("s_waitcnt vmcnt(" #n ")" ::: "memory")
; #define PG8_WAIT_L(n) asm volatile("s_waitcnt lgkmcnt(" #n ")" ::: "memory")
; #define PG8_BAR __builtin_amdgcn_s_barrier()
; #define PG8_SCHED __builtin_amdgcn_sched_barrier(0)
; template <class Epi, class Sched, bool ALIGN_EPI = false, bool SP2 = false>
; __device__ __forceinline__ void gemm_phase(PG8_LAS unsigned char* lds, const Gemm g, const Sched& S, const Epi& E, const int tid) {
;     ...
;             PG8_WAIT_V(8); PG8_WAIT_L(0); PG8_BAR; PG8_MMA(0, 0, At, B0); PG8_MMA(0, 1, At, B1); PG8_BAR; PG8_SCHED;
;             PG8_LDA(At, 1, 1); PG8_STAGE(PG8_SB(1, 0), b3, voffB); PG8_STAGE(PG8_SB(1, 1), b3 + hstep, voffB); PG8_STAGE(PG8_SA(1, 0), a3, voffA);
;             PG8_WAIT_V(8); PG8_WAIT_L(0); PG8_BAR; PG8_MMA(1, 0, At, B0); PG8_MMA(1, 1, At, B1); PG8_BAR; PG8_SCHED;
	s_setprio 0
	s_add_i32 s64, s86, s2
	v_lshl_add_u64 v[124:125], v[218:219], 0, s[66:67]
	s_mov_b32 m0, s64
	ds_read_b128 v[120:123], v245 offset:49152
	ds_read_b128 v[184:187], v245 offset:50176
	ds_read_b128 v[188:191], v245 offset:51200
	ds_read_b128 v[192:195], v245 offset:52224
	ds_read_b128 v[202:205], v245 offset:53248
	ds_read_b128 v[206:209], v245 offset:54272
	ds_read_b128 v[210:213], v245 offset:55296
	ds_read_b128 v[214:217], v245 offset:56320
	global_load_lds_dwordx4 v[124:125], off
	s_add_i32 m0, s64, 0x2000
	s_add_u32 s34, s34, 0x40080
	v_lshl_add_u64 v[124:125], v[220:221], 0, s[66:67]
	s_addc_u32 s35, s35, 0
	s_add_i32 s64, s87, s2
	global_load_lds_dwordx4 v[124:125], off
	v_lshl_add_u64 v[124:125], s[34:35], 0, v[166:167]
	s_mov_b32 m0, s64
	s_nop 0
	global_load_lds_dwordx4 v[124:125], off
	v_lshl_add_u64 v[124:125], s[34:35], 0, v[0:1]
	s_add_i32 m0, s64, 0x2000
	s_nop 0
	global_load_lds_dwordx4 v[124:125], off
	v_lshl_add_u64 v[124:125], v[222:223], 0, s[66:67]
	s_mov_b32 m0, s51
	s_nop 0
	global_load_lds_dwordx4 v[124:125], off
	v_lshl_add_u64 v[124:125], v[224:225], 0, s[66:67]
	s_mov_b32 m0, s30
	s_nop 0
	global_load_lds_dwordx4 v[124:125], off
	s_waitcnt vmcnt(8)
	s_waitcnt lgkmcnt(0)
	s_setprio 1
	s_barrier
	v_mfma_f32_16x16x32_bf16 v[124:127], v[92:95], v[120:123], v[128:131]
	v_mfma_f32_16x16x32_bf16 v[116:119], v[100:103], v[120:123], v[116:119]
	v_mfma_f32_16x16x32_bf16 v[32:35], v[92:95], v[188:191], v[32:35]
	v_mfma_f32_16x16x32_bf16 v[28:31], v[100:103], v[188:191], v[28:31]
	v_mfma_f32_16x16x32_bf16 v[20:23], v[92:95], v[202:205], v[20:23]
	v_mfma_f32_16x16x32_bf16 v[16:19], v[100:103], v[202:205], v[16:19]
	v_mfma_f32_16x16x32_bf16 v[80:83], v[92:95], v[210:213], v[80:83]
	v_mfma_f32_16x16x32_bf16 v[72:75], v[100:103], v[210:213], v[72:75]
	v_mfma_f32_16x16x32_bf16 v[128:131], v[96:99], v[184:187], v[124:127]
	v_mfma_f32_16x16x32_bf16 v[116:119], v[104:107], v[184:187], v[116:119]
	v_mfma_f32_16x16x32_bf16 v[32:35], v[96:99], v[192:195], v[32:35]
	v_mfma_f32_16x16x32_bf16 v[28:31], v[104:107], v[192:195], v[28:31]
	v_mfma_f32_16x16x32_bf16 v[20:23], v[96:99], v[206:209], v[20:23]
	v_mfma_f32_16x16x32_bf16 v[16:19], v[104:107], v[206:209], v[16:19]
	v_mfma_f32_16x16x32_bf16 v[80:83], v[96:99], v[214:217], v[80:83]
	v_mfma_f32_16x16x32_bf16 v[72:75], v[104:107], v[214:217], v[72:75]
	s_setprio 0
	s_setprio 1
	v_mfma_f32_16x16x32_bf16 v[84:87], v[108:111], v[120:123], v[84:87]
	v_mfma_f32_16x16x32_bf16 v[124:127], v[112:115], v[184:187], v[84:87]
	v_mfma_f32_16x16x32_bf16 v[84:87], v[176:179], v[120:123], v[88:91]
	v_mfma_f32_16x16x32_bf16 v[24:27], v[108:111], v[188:191], v[24:27]
	v_mfma_f32_16x16x32_bf16 v[12:15], v[176:179], v[188:191], v[12:15]
	v_mfma_f32_16x16x32_bf16 v[8:11], v[108:111], v[202:205], v[8:11]
	v_mfma_f32_16x16x32_bf16 v[4:7], v[176:179], v[202:205], v[4:7]
	v_mfma_f32_16x16x32_bf16 v[76:79], v[108:111], v[210:213], v[76:79]
	v_mfma_f32_16x16x32_bf16 v[68:71], v[176:179], v[210:213], v[68:71]
	v_mfma_f32_16x16x32_bf16 v[120:123], v[180:183], v[184:187], v[84:87]
	v_mfma_f32_16x16x32_bf16 v[24:27], v[112:115], v[192:195], v[24:27]
	v_mfma_f32_16x16x32_bf16 v[12:15], v[180:183], v[192:195], v[12:15]
	v_mfma_f32_16x16x32_bf16 v[8:11], v[112:115], v[206:209], v[8:11]
	v_mfma_f32_16x16x32_bf16 v[4:7], v[180:183], v[206:209], v[4:7]
	v_mfma_f32_16x16x32_bf16 v[76:79], v[112:115], v[214:217], v[76:79]
	v_mfma_f32_16x16x32_bf16 v[68:71], v[180:183], v[214:217], v[68:71]
	s_barrier
	s_setprio 0
	s_add_i32 s85, s85, 2
	s_add_u32 s18, s18, 0x100
	s_addc_u32 s19, s19, 0
	s_add_u32 s24, s24, 0x100
	s_addc_u32 s84, s84, 0
	s_cmp_gt_u32 s85, 13
	s_cbranch_scc0 .LBB0_35
	s_and_b64 vcc, exec, s[54:55]
	s_cbranch_vccz .LBB0_38
	s_barrier

; #define PG8_STAGE(bufoff, gbase, voff) do { _Pragma("unroll") for (int _i = 0; _i < 2; ++_i) \
;         __builtin_amdgcn_global_load_lds((const unsigned*)((const char*)(gbase) + (voff)[_i]), (PG8_LAS unsigned*)(lds + (bufoff) + ldsw + _i * 8192), 16, 0, 0); } while (0)
; #define PG8_LDA(dst, b, h) do { _Pragma("unroll") for (int m = 0; m < 4; ++m) _Pragma("unroll") for (int k = 0; k < 2; ++k) dst[m][k] = *(const PG8_LAS bf16x8*)(lds + PG8_SA(b, h) + aoff + m * 2048 + k * 1024); } while (0)
; #define PG8_LDB(dst, b, h) do { _Pragma("unroll") for (int n = 0; n < 2; ++n) _Pragma("unroll") for (int k = 0; k < 2; ++k) dst[n][k] = *(const PG8_LAS bf16x8*)(lds + PG8_SB(b, h) + boff + n * 2048 + k * 1024); } while (0)
; #define PG8_MMA(ai, bj, At, Bt) do { __builtin_amdgcn_s_setprio(1); _Pragma("unroll") for (int m = 0; m < 4; ++m) _Pragma("unroll") for (int n = 0; n < 2; ++n) _Pragma("unroll") for (int k = 0; k < 2; ++k) \
;         acc[ai][bj][m][n] = __builtin_amdgcn_mfma_f32_16x16x32_bf16(Bt[n][k], At[m][k], acc[ai][bj][m][n], 0, 0, 0); __builtin_amdgcn_s_setprio(0); } while (0)
; #define PG8_WAIT_V(n) asm volatile("s_waitcnt vmcnt(" #n ")" ::: "memory")
; #define PG8_WAIT_L(n) asm volatile("s_waitcnt lgkmcnt(" #n ")" ::: "memory")
; #define PG8_BAR __builtin_amdgcn_s_barrier()
; #define PG8_SCHED __builtin_amdgcn_sched_barrier(0)
; template <class Epi, class Sched, bool ALIGN_EPI = false, bool SP2 = false>
; __device__ __forceinline__ void gemm_phase(PG8_LAS unsigned char* lds, const Gemm g, const Sched& S, const Epi& E, const int tid) {
;     ...
;             PG8_LDB(B0, 0, 0); PG8_LDB(B1, 0, 1); PG8_SCHED; PG8_LDA(At, 0, 0); PG8_STAGE(PG8_SA(1, 1), a1 + hstep, voffA);
;             PG8_WAIT_V(8); PG8_WAIT_L(0); PG8_BAR; PG8_MMA(0, 0, At, B0); PG8_MMA(0, 1, At, B1); PG8_BAR; PG8_SCHED;
;             PG8_LDA(At, 0, 1); PG8_STAGE(PG8_SB(0, 0), b2, voffB); PG8_STAGE(PG8_SB(0, 1), b2 + hstep, voffB); PG8_STAGE(PG8_SA(0, 0), a2, voffA);
;             PG8_WAIT_V(8); PG8_WAIT_L(0); PG8_BAR; PG8_MMA(1, 0, At, B0); PG8_MMA(1, 1, At, B1); PG8_BAR; PG8_SCHED;
.LBB0_64:
	s_add_u32 s44, vcc_lo, 0xfffc0080
	s_addc_u32 s45, vcc_hi, -1
	s_add_i32 s86, 0, 0x10000
	s_cmp_eq_u32 s85, 12
	s_cselect_b32 s63, s43, s45
	s_cselect_b32 s62, s47, s44
	s_cselect_b32 s45, s19, s84
	s_cselect_b32 s44, s61, s24
	s_add_i32 s88, 0, 0x14000
	v_add_u32_e32 v144, s86, v228
	v_add_u32_e32 v160, s88, v228
	ds_read_b128 v[132:135], v144
	ds_read_b128 v[136:139], v144 offset:1024
	ds_read_b128 v[140:143], v144 offset:2048
	ds_read_b128 v[144:147], v144 offset:3072
	ds_read_b128 v[148:151], v160
	ds_read_b128 v[152:155], v160 offset:1024
	ds_read_b128 v[156:159], v160 offset:2048
	ds_read_b128 v[160:163], v160 offset:3072
	v_lshl_add_u64 v[212:213], vcc, 0, v[208:209]
	s_add_i32 m0, s25, 0xc000
	ds_read_b128 v[164:167], v230
	ds_read_b128 v[168:171], v230 offset:1024
	ds_read_b128 v[172:175], v230 offset:2048
	ds_read_b128 v[176:179], v230 offset:3072
	ds_read_b128 v[180:183], v230 offset:4096
	ds_read_b128 v[184:187], v230 offset:5120
	ds_read_b128 v[188:191], v230 offset:6144
	ds_read_b128 v[192:195], v230 offset:7168
	global_load_lds_dwordx4 v[212:213], off
	v_lshl_add_u64 v[212:213], vcc, 0, v[210:211]
	s_add_i32 m0, s25, 0xe000
	s_nop 0
	global_load_lds_dwordx4 v[212:213], off
	s_waitcnt vmcnt(8)
	s_waitcnt lgkmcnt(0)
	s_setprio 1
	s_barrier
	v_mfma_f32_16x16x32_bf16 v[128:131], v[132:135], v[164:167], v[128:131]
	v_mfma_f32_16x16x32_bf16 v[124:127], v[140:143], v[164:167], v[124:127]
	v_mfma_f32_16x16x32_bf16 v[112:115], v[132:135], v[172:175], v[112:115]
	v_mfma_f32_16x16x32_bf16 v[108:111], v[140:143], v[172:175], v[108:111]
	v_mfma_f32_16x16x32_bf16 v[96:99], v[132:135], v[180:183], v[96:99]
	v_mfma_f32_16x16x32_bf16 v[92:95], v[140:143], v[180:183], v[92:95]
	v_mfma_f32_16x16x32_bf16 v[80:83], v[132:135], v[188:191], v[80:83]
	v_mfma_f32_16x16x32_bf16 v[76:79], v[140:143], v[188:191], v[76:79]
	v_mfma_f32_16x16x32_bf16 v[128:131], v[136:139], v[168:171], v[128:131]
	v_mfma_f32_16x16x32_bf16 v[124:127], v[144:147], v[168:171], v[124:127]
	v_mfma_f32_16x16x32_bf16 v[112:115], v[136:139], v[176:179], v[112:115]
	v_mfma_f32_16x16x32_bf16 v[108:111], v[144:147], v[176:179], v[108:111]
	v_mfma_f32_16x16x32_bf16 v[96:99], v[136:139], v[184:187], v[96:99]
	v_mfma_f32_16x16x32_bf16 v[92:95], v[144:147], v[184:187], v[92:95]
	v_mfma_f32_16x16x32_bf16 v[80:83], v[136:139], v[192:195], v[80:83]
	v_mfma_f32_16x16x32_bf16 v[76:79], v[144:147], v[192:195], v[76:79]
	s_setprio 0
	s_setprio 1
	v_mfma_f32_16x16x32_bf16 v[120:123], v[148:151], v[164:167], v[120:123]
	v_mfma_f32_16x16x32_bf16 v[116:119], v[156:159], v[164:167], v[116:119]
	v_mfma_f32_16x16x32_bf16 v[104:107], v[148:151], v[172:175], v[104:107]
	v_mfma_f32_16x16x32_bf16 v[100:103], v[156:159], v[172:175], v[100:103]
	v_mfma_f32_16x16x32_bf16 v[88:91], v[148:151], v[180:183], v[88:91]
	v_mfma_f32_16x16x32_bf16 v[84:87], v[156:159], v[180:183], v[84:87]
	v_mfma_f32_16x16x32_bf16 v[72:75], v[148:151], v[188:191], v[72:75]
	v_mfma_f32_16x16x32_bf16 v[68:71], v[156:159], v[188:191], v[68:71]
	v_mfma_f32_16x16x32_bf16 v[120:123], v[152:155], v[168:171], v[120:123]
	v_mfma_f32_16x16x32_bf16 v[116:119], v[160:163], v[168:171], v[116:119]
	v_mfma_f32_16x16x32_bf16 v[104:107], v[152:155], v[176:179], v[104:107]
	v_mfma_f32_16x16x32_bf16 v[100:103], v[160:163], v[176:179], v[100:103]
	v_mfma_f32_16x16x32_bf16 v[88:91], v[152:155], v[184:187], v[88:91]
	v_mfma_f32_16x16x32_bf16 v[84:87], v[160:163], v[184:187], v[84:87]
	v_mfma_f32_16x16x32_bf16 v[72:75], v[152:155], v[192:195], v[72:75]
	v_mfma_f32_16x16x32_bf16 v[68:71], v[160:163], v[192:195], v[68:71]
	s_barrier
	s_setprio 0
	s_add_i32 s86, s86, s2
	v_lshl_add_u64 v[212:213], s[44:45], 0, v[202:203]
	s_mov_b32 m0, s86
	ds_read_b128 v[164:167], v230 offset:16384
	ds_read_b128 v[168:171], v230 offset:17408
	ds_read_b128 v[172:175], v230 offset:18432
	ds_read_b128 v[176:179], v230 offset:19456
	ds_read_b128 v[180:183], v230 offset:20480
	ds_read_b128 v[184:187], v230 offset:21504
	ds_read_b128 v[188:191], v230 offset:22528
	ds_read_b128 v[192:195], v230 offset:23552
	global_load_lds_dwordx4 v[212:213], off
	s_add_i32 m0, s86, 0x2000
	s_add_u32 s86, s44, 0x40000
	v_lshl_add_u64 v[214:215], s[44:45], 0, v[206:207]
	s_addc_u32 s87, s45, 0
	s_add_i32 s88, s88, s2
	global_load_lds_dwordx4 v[214:215], off
	v_lshl_add_u64 v[216:217], s[86:87], 0, v[202:203]
	s_mov_b32 m0, s88
	v_lshl_add_u64 v[218:219], s[62:63], 0, v[204:205]
	global_load_lds_dwordx4 v[216:217], off
	v_lshl_add_u64 v[216:217], s[86:87], 0, v[206:207]
	s_add_i32 m0, s88, 0x2000
	s_nop 0
	global_load_lds_dwordx4 v[216:217], off
	v_lshl_add_u64 v[216:217], s[62:63], 0, v[0:1]
	s_mov_b32 m0, s25
	s_nop 0
	global_load_lds_dwordx4 v[216:217], off
	s_mov_b32 m0, s28
	s_nop 0
	global_load_lds_dwordx4 v[218:219], off
	s_waitcnt vmcnt(8)
	s_waitcnt lgkmcnt(0)
	s_setprio 1
	s_barrier
; #define PG8_STAGE(bufoff, gbase, voff) do { _Pragma("unroll") for (int _i = 0; _i < 2; ++_i) \
;         __builtin_amdgcn_global_load_lds((const unsigned*)((const char*)(gbase) + (voff)[_i]), (PG8_LAS unsigned*)(lds + (bufoff) + ldsw + _i * 8192), 16, 0, 0); } while (0)
; #define PG8_LDA(dst, b, h) do { _Pragma("unroll") for (int m = 0; m < 4; ++m) _Pragma("unroll") for (int k = 0; k < 2; ++k) dst[m][k] = *(const PG8_LAS bf16x8*)(lds + PG8_SA(b, h) + aoff + m * 2048 + k * 1024); } while (0)
; #define PG8_LDB(dst, b, h) do { _Pragma("unroll") for (int n = 0; n < 2; ++n) _Pragma("unroll") for (int k = 0; k < 2; ++k) dst[n][k] = *(const PG8_LAS bf16x8*)(lds + PG8_SB(b, h) + boff + n * 2048 + k * 1024); } while (0)
; #define PG8_MMA(ai, bj, At, Bt) do { __builtin_amdgcn_s_setprio(1); _Pragma("unroll") for (int m = 0; m < 4; ++m) _Pragma("unroll") for (int n = 0; n < 2; ++n) _Pragma("unroll") for (int k = 0; k < 2; ++k) \
;         acc[ai][bj][m][n] = __builtin_amdgcn_mfma_f32_16x16x32_bf16(Bt[n][k], At[m][k], acc[ai][bj][m][n], 0, 0, 0); __builtin_amdgcn_s_setprio(0); } while (0)
; #define PG8_WAIT_V(n) asm volatile("s_waitcnt vmcnt(" #n ")" ::: "memory")
; #define PG8_WAIT_L(n) asm volatile("s_waitcnt lgkmcnt(" #n ")" ::: "memory")
; #define PG8_BAR __builtin_amdgcn_s_barrier()
; #define PG8_SCHED __builtin_amdgcn_sched_barrier(0)
; template <class Epi, class Sched, bool ALIGN_EPI = false, bool SP2 = false>
; __device__ __forceinline__ void gemm_phase(PG8_LAS unsigned char* lds, const Gemm g, const Sched& S, const Epi& E, const int tid) {
;     ...
;             PG8_WAIT_V(8); PG8_WAIT_L(0); PG8_BAR; PG8_MMA(1, 0, At, B0); PG8_MMA(1, 1, At, B1); PG8_BAR; PG8_SCHED;
;             PG8_LDB(B0, 1, 0); PG8_LDB(B1, 1, 1); PG8_SCHED; PG8_LDA(At, 1, 0); PG8_STAGE(PG8_SA(0, 1), a2 + hstep, voffA);
;             PG8_WAIT_V(8); PG8_WAIT_L(0); PG8_BAR; PG8_MMA(0, 0, At, B0); PG8_MMA(0, 1, At, B1); PG8_BAR; PG8_SCHED;
	v_mfma_f32_16x16x32_bf16 v[64:67], v[132:135], v[164:167], v[64:67]
	v_mfma_f32_16x16x32_bf16 v[60:63], v[140:143], v[164:167], v[60:63]
	v_mfma_f32_16x16x32_bf16 v[48:51], v[132:135], v[172:175], v[48:51]
	v_mfma_f32_16x16x32_bf16 v[44:47], v[140:143], v[172:175], v[44:47]
	v_mfma_f32_16x16x32_bf16 v[32:35], v[132:135], v[180:183], v[32:35]
	v_mfma_f32_16x16x32_bf16 v[28:31], v[140:143], v[180:183], v[28:31]
	v_mfma_f32_16x16x32_bf16 v[16:19], v[132:135], v[188:191], v[16:19]
	v_mfma_f32_16x16x32_bf16 v[12:15], v[140:143], v[188:191], v[12:15]
	v_mfma_f32_16x16x32_bf16 v[64:67], v[136:139], v[168:171], v[64:67]
	v_mfma_f32_16x16x32_bf16 v[60:63], v[144:147], v[168:171], v[60:63]
	v_mfma_f32_16x16x32_bf16 v[48:51], v[136:139], v[176:179], v[48:51]
	v_mfma_f32_16x16x32_bf16 v[44:47], v[144:147], v[176:179], v[44:47]
	v_mfma_f32_16x16x32_bf16 v[32:35], v[136:139], v[184:187], v[32:35]
	v_mfma_f32_16x16x32_bf16 v[28:31], v[144:147], v[184:187], v[28:31]
	v_mfma_f32_16x16x32_bf16 v[16:19], v[136:139], v[192:195], v[16:19]
	v_mfma_f32_16x16x32_bf16 v[12:15], v[144:147], v[192:195], v[12:15]
	s_setprio 0
	s_setprio 1
	v_mfma_f32_16x16x32_bf16 v[56:59], v[148:151], v[164:167], v[56:59]
	v_mfma_f32_16x16x32_bf16 v[52:55], v[156:159], v[164:167], v[52:55]
	v_mfma_f32_16x16x32_bf16 v[40:43], v[148:151], v[172:175], v[40:43]
	v_mfma_f32_16x16x32_bf16 v[36:39], v[156:159], v[172:175], v[36:39]
	v_mfma_f32_16x16x32_bf16 v[24:27], v[148:151], v[180:183], v[24:27]
	v_mfma_f32_16x16x32_bf16 v[20:23], v[156:159], v[180:183], v[20:23]
	v_mfma_f32_16x16x32_bf16 v[8:11], v[148:151], v[188:191], v[8:11]
	v_mfma_f32_16x16x32_bf16 v[4:7], v[156:159], v[188:191], v[4:7]
	v_mfma_f32_16x16x32_bf16 v[56:59], v[152:155], v[168:171], v[56:59]
	v_mfma_f32_16x16x32_bf16 v[52:55], v[160:163], v[168:171], v[52:55]
	v_mfma_f32_16x16x32_bf16 v[40:43], v[152:155], v[176:179], v[40:43]
	v_mfma_f32_16x16x32_bf16 v[36:39], v[160:163], v[176:179], v[36:39]
	v_mfma_f32_16x16x32_bf16 v[24:27], v[152:155], v[184:187], v[24:27]
	v_mfma_f32_16x16x32_bf16 v[20:23], v[160:163], v[184:187], v[20:23]
	v_mfma_f32_16x16x32_bf16 v[8:11], v[152:155], v[192:195], v[8:11]
	v_mfma_f32_16x16x32_bf16 v[4:7], v[160:163], v[192:195], v[4:7]
	s_barrier
	s_setprio 0
	s_add_i32 s86, 0, 0x18000
	s_add_i32 s87, 0, 0x1c000
	v_add_u32_e32 v144, s86, v228
	v_add_u32_e32 v160, s87, v228
	ds_read_b128 v[132:135], v144
	ds_read_b128 v[136:139], v144 offset:1024
	ds_read_b128 v[140:143], v144 offset:2048
	ds_read_b128 v[144:147], v144 offset:3072
	ds_read_b128 v[148:151], v160
	ds_read_b128 v[152:155], v160 offset:1024
	ds_read_b128 v[156:159], v160 offset:2048
	ds_read_b128 v[160:163], v160 offset:3072
	s_add_u32 s62, s62, 0x40000
	s_addc_u32 s63, s63, 0
	s_mov_b32 m0, s29
	v_lshl_add_u64 v[220:221], s[62:63], 0, v[0:1]
	ds_read_b128 v[164:167], v230 offset:32768
	ds_read_b128 v[168:171], v230 offset:33792
	ds_read_b128 v[172:175], v230 offset:34816
	ds_read_b128 v[176:179], v230 offset:35840
	ds_read_b128 v[180:183], v230 offset:36864
	ds_read_b128 v[184:187], v230 offset:37888
	ds_read_b128 v[188:191], v230 offset:38912
	ds_read_b128 v[192:195], v230 offset:39936
	global_load_lds_dwordx4 v[220:221], off
	v_lshl_add_u64 v[220:221], s[62:63], 0, v[204:205]
	s_mov_b32 m0, s30
	s_nop 0
	global_load_lds_dwordx4 v[220:221], off
	s_waitcnt vmcnt(8)
	s_waitcnt lgkmcnt(0)
	s_setprio 1
	s_barrier
	v_mfma_f32_16x16x32_bf16 v[128:131], v[132:135], v[164:167], v[128:131]
	v_mfma_f32_16x16x32_bf16 v[124:127], v[140:143], v[164:167], v[124:127]
	v_mfma_f32_16x16x32_bf16 v[112:115], v[132:135], v[172:175], v[112:115]
	v_mfma_f32_16x16x32_bf16 v[108:111], v[140:143], v[172:175], v[108:111]
	v_mfma_f32_16x16x32_bf16 v[96:99], v[132:135], v[180:183], v[96:99]
	v_mfma_f32_16x16x32_bf16 v[92:95], v[140:143], v[180:183], v[92:95]
	v_mfma_f32_16x16x32_bf16 v[80:83], v[132:135], v[188:191], v[80:83]
	v_mfma_f32_16x16x32_bf16 v[76:79], v[140:143], v[188:191], v[76:79]
	v_mfma_f32_16x16x32_bf16 v[128:131], v[136:139], v[168:171], v[128:131]
	v_mfma_f32_16x16x32_bf16 v[124:127], v[144:147], v[168:171], v[124:127]
	v_mfma_f32_16x16x32_bf16 v[112:115], v[136:139], v[176:179], v[112:115]
	v_mfma_f32_16x16x32_bf16 v[108:111], v[144:147], v[176:179], v[108:111]
	v_mfma_f32_16x16x32_bf16 v[96:99], v[136:139], v[184:187], v[96:99]
	v_mfma_f32_16x16x32_bf16 v[92:95], v[144:147], v[184:187], v[92:95]
	v_mfma_f32_16x16x32_bf16 v[80:83], v[136:139], v[192:195], v[80:83]
	v_mfma_f32_16x16x32_bf16 v[76:79], v[144:147], v[192:195], v[76:79]
	s_setprio 0
	s_setprio 1
	v_mfma_f32_16x16x32_bf16 v[120:123], v[148:151], v[164:167], v[120:123]
	v_mfma_f32_16x16x32_bf16 v[116:119], v[156:159], v[164:167], v[116:119]
	v_mfma_f32_16x16x32_bf16 v[104:107], v[148:151], v[172:175], v[104:107]
	v_mfma_f32_16x16x32_bf16 v[100:103], v[156:159], v[172:175], v[100:103]
	v_mfma_f32_16x16x32_bf16 v[88:91], v[148:151], v[180:183], v[88:91]
	v_mfma_f32_16x16x32_bf16 v[84:87], v[156:159], v[180:183], v[84:87]
	v_mfma_f32_16x16x32_bf16 v[72:75], v[148:151], v[188:191], v[72:75]
	v_mfma_f32_16x16x32_bf16 v[68:71], v[156:159], v[188:191], v[68:71]
	v_mfma_f32_16x16x32_bf16 v[120:123], v[152:155], v[168:171], v[120:123]
	v_mfma_f32_16x16x32_bf16 v[116:119], v[160:163], v[168:171], v[116:119]
	v_mfma_f32_16x16x32_bf16 v[104:107], v[152:155], v[176:179], v[104:107]
	v_mfma_f32_16x16x32_bf16 v[100:103], v[160:163], v[176:179], v[100:103]
	v_mfma_f32_16x16x32_bf16 v[88:91], v[152:155], v[184:187], v[88:91]
	v_mfma_f32_16x16x32_bf16 v[84:87], v[160:163], v[184:187], v[84:87]
	v_mfma_f32_16x16x32_bf16 v[72:75], v[152:155], v[192:195], v[72:75]
	v_mfma_f32_16x16x32_bf16 v[68:71], v[160:163], v[192:195], v[68:71]
	s_barrier
; #define PG8_STAGE(bufoff, gbase, voff) do { _Pragma("unroll") for (int _i = 0; _i < 2; ++_i) \
;         __builtin_amdgcn_global_load_lds((const unsigned*)((const char*)(gbase) + (voff)[_i]), (PG8_LAS unsigned*)(lds + (bufoff) + ldsw + _i * 8192), 16, 0, 0); } while (0)
; #define PG8_LDA(dst, b, h) do { _Pragma("unroll") for (int m = 0; m < 4; ++m) _Pragma("unroll") for (int k = 0; k < 2; ++k) dst[m][k] = *(const PG8_LAS bf16x8*)(lds + PG8_SA(b, h) + aoff + m * 2048 + k * 1024); } while (0)
; #define PG8_MMA(ai, bj, At, Bt) do { __builtin_amdgcn_s_setprio(1); _Pragma("unroll") for (int m = 0; m < 4; ++m) _Pragma("unroll") for (int n = 0; n < 2; ++n) _Pragma("unroll") for (int k = 0; k < 2; ++k) \
;         acc[ai][bj][m][n] = __builtin_amdgcn_mfma_f32_16x16x32_bf16(Bt[n][k], At[m][k], acc[ai][bj][m][n], 0, 0, 0); __builtin_amdgcn_s_setprio(0); } while (0)
; #define PG8_WAIT_V(n) asm volatile("s_waitcnt vmcnt(" #n ")" ::: "memory")
; #define PG8_WAIT_L(n) asm volatile("s_waitcnt lgkmcnt(" #n ")" ::: "memory")
; #define PG8_BAR __builtin_amdgcn_s_barrier()
; #define PG8_SCHED __builtin_amdgcn_sched_barrier(0)
; template <class Epi, class Sched, bool ALIGN_EPI = false, bool SP2 = false>
; __device__ __forceinline__ void gemm_phase(PG8_LAS unsigned char* lds, const Gemm g, const Sched& S, const Epi& E, const int tid) {
;     ...
;             PG8_LDA(At, 1, 1); PG8_STAGE(PG8_SB(1, 0), b3, voffB); PG8_STAGE(PG8_SB(1, 1), b3 + hstep, voffB); PG8_STAGE(PG8_SA(1, 0), a3, voffA);
;             PG8_WAIT_V(8); PG8_WAIT_L(0); PG8_BAR; PG8_MMA(1, 0, At, B0); PG8_MMA(1, 1, At, B1); PG8_BAR; PG8_SCHED;
	s_setprio 0
	s_add_i32 s62, s86, s2
	v_lshl_add_u64 v[212:213], v[212:213], 0, s[66:67]
	s_mov_b32 m0, s62
	ds_read_b128 v[164:167], v230 offset:49152
	ds_read_b128 v[168:171], v230 offset:50176
	ds_read_b128 v[172:175], v230 offset:51200
	ds_read_b128 v[176:179], v230 offset:52224
	ds_read_b128 v[180:183], v230 offset:53248
	ds_read_b128 v[184:187], v230 offset:54272
	ds_read_b128 v[188:191], v230 offset:55296
	ds_read_b128 v[192:195], v230 offset:56320
	global_load_lds_dwordx4 v[212:213], off
	s_add_i32 m0, s62, 0x2000
	s_add_u32 s44, s44, 0x40080
	v_lshl_add_u64 v[212:213], v[214:215], 0, s[66:67]
	s_addc_u32 s45, s45, 0
	s_add_i32 s62, s87, s2
	global_load_lds_dwordx4 v[212:213], off
	v_lshl_add_u64 v[212:213], s[44:45], 0, v[202:203]
	s_mov_b32 m0, s62
	s_nop 0
	global_load_lds_dwordx4 v[212:213], off
	v_lshl_add_u64 v[212:213], s[44:45], 0, v[206:207]
	s_add_i32 m0, s62, 0x2000
	s_nop 0
	global_load_lds_dwordx4 v[212:213], off
	v_lshl_add_u64 v[212:213], v[216:217], 0, s[66:67]
	s_mov_b32 m0, s31
	s_nop 0
	global_load_lds_dwordx4 v[212:213], off
	v_lshl_add_u64 v[212:213], v[218:219], 0, s[66:67]
	s_mov_b32 m0, s59
	s_nop 0
	global_load_lds_dwordx4 v[212:213], off
	s_waitcnt vmcnt(8)
	s_waitcnt lgkmcnt(0)
	s_setprio 1
	s_barrier
	v_mfma_f32_16x16x32_bf16 v[64:67], v[132:135], v[164:167], v[64:67]
	v_mfma_f32_16x16x32_bf16 v[60:63], v[140:143], v[164:167], v[60:63]
	v_mfma_f32_16x16x32_bf16 v[48:51], v[132:135], v[172:175], v[48:51]
	v_mfma_f32_16x16x32_bf16 v[44:47], v[140:143], v[172:175], v[44:47]
	v_mfma_f32_16x16x32_bf16 v[32:35], v[132:135], v[180:183], v[32:35]
	v_mfma_f32_16x16x32_bf16 v[28:31], v[140:143], v[180:183], v[28:31]
	v_mfma_f32_16x16x32_bf16 v[16:19], v[132:135], v[188:191], v[16:19]
	v_mfma_f32_16x16x32_bf16 v[12:15], v[140:143], v[188:191], v[12:15]
	v_mfma_f32_16x16x32_bf16 v[64:67], v[136:139], v[168:171], v[64:67]
	v_mfma_f32_16x16x32_bf16 v[60:63], v[144:147], v[168:171], v[60:63]
	v_mfma_f32_16x16x32_bf16 v[48:51], v[136:139], v[176:179], v[48:51]
	v_mfma_f32_16x16x32_bf16 v[44:47], v[144:147], v[176:179], v[44:47]
	v_mfma_f32_16x16x32_bf16 v[32:35], v[136:139], v[184:187], v[32:35]
	v_mfma_f32_16x16x32_bf16 v[28:31], v[144:147], v[184:187], v[28:31]
	v_mfma_f32_16x16x32_bf16 v[16:19], v[136:139], v[192:195], v[16:19]
	v_mfma_f32_16x16x32_bf16 v[12:15], v[144:147], v[192:195], v[12:15]
	s_setprio 0
	s_setprio 1
	v_mfma_f32_16x16x32_bf16 v[56:59], v[148:151], v[164:167], v[56:59]
	v_mfma_f32_16x16x32_bf16 v[52:55], v[156:159], v[164:167], v[52:55]
	v_mfma_f32_16x16x32_bf16 v[40:43], v[148:151], v[172:175], v[40:43]
	v_mfma_f32_16x16x32_bf16 v[36:39], v[156:159], v[172:175], v[36:39]
	v_mfma_f32_16x16x32_bf16 v[24:27], v[148:151], v[180:183], v[24:27]
	v_mfma_f32_16x16x32_bf16 v[20:23], v[156:159], v[180:183], v[20:23]
	v_mfma_f32_16x16x32_bf16 v[8:11], v[148:151], v[188:191], v[8:11]
	v_mfma_f32_16x16x32_bf16 v[4:7], v[156:159], v[188:191], v[4:7]
	v_mfma_f32_16x16x32_bf16 v[56:59], v[152:155], v[168:171], v[56:59]
	v_mfma_f32_16x16x32_bf16 v[52:55], v[160:163], v[168:171], v[52:55]
	v_mfma_f32_16x16x32_bf16 v[40:43], v[152:155], v[176:179], v[40:43]
	v_mfma_f32_16x16x32_bf16 v[36:39], v[160:163], v[176:179], v[36:39]
	v_mfma_f32_16x16x32_bf16 v[24:27], v[152:155], v[184:187], v[24:27]
	v_mfma_f32_16x16x32_bf16 v[20:23], v[160:163], v[184:187], v[20:23]
	v_mfma_f32_16x16x32_bf16 v[8:11], v[152:155], v[192:195], v[8:11]
	v_mfma_f32_16x16x32_bf16 v[4:7], v[160:163], v[192:195], v[4:7]
	s_barrier
	s_setprio 0
	s_add_i32 s85, s85, 2
	s_add_u32 vcc_lo, vcc_lo, 0x100
	s_addc_u32 vcc_hi, vcc_hi, 0
	s_add_u32 s24, s24, 0x100
	s_addc_u32 s84, s84, 0
	s_cmp_gt_u32 s85, 13
	s_cbranch_scc0 .LBB0_64
	s_and_b64 vcc, exec, s[56:57]
	s_cbranch_vccz .LBB0_67
	s_barrier

; #define PG8_STAGE(bufoff, gbase, voff) do { _Pragma("unroll") for (int _i = 0; _i < 2; ++_i) \
;         __builtin_amdgcn_global_load_lds((const unsigned*)((const char*)(gbase) + (voff)[_i]), (PG8_LAS unsigned*)(lds + (bufoff) + ldsw + _i * 8192), 16, 0, 0); } while (0)
; #define PG8_LDA(dst, b, h) do { _Pragma("unroll") for (int m = 0; m < 4; ++m) _Pragma("unroll") for (int k = 0; k < 2; ++k) dst[m][k] = *(const PG8_LAS bf16x8*)(lds + PG8_SA(b, h) + aoff + m * 2048 + k * 1024); } while (0)
; #define PG8_LDB(dst, b, h) do { _Pragma("unroll") for (int n = 0; n < 2; ++n) _Pragma("unroll") for (int k = 0; k < 2; ++k) dst[n][k] = *(const PG8_LAS bf16x8*)(lds + PG8_SB(b, h) + boff + n * 2048 + k * 1024); } while (0)
; #define PG8_MMA(ai, bj, At, Bt) do { __builtin_amdgcn_s_setprio(1); _Pragma("unroll") for (int m = 0; m < 4; ++m) _Pragma("unroll") for (int n = 0; n < 2; ++n) _Pragma("unroll") for (int k = 0; k < 2; ++k) \
;         acc[ai][bj][m][n] = __builtin_amdgcn_mfma_f32_16x16x32_bf16(Bt[n][k], At[m][k], acc[ai][bj][m][n], 0, 0, 0); __builtin_amdgcn_s_setprio(0); } while (0)
; #define PG8_WAIT_V(n) asm volatile("s_waitcnt vmcnt(" #n ")" ::: "memory")
; #define PG8_WAIT_L(n) asm volatile("s_waitcnt lgkmcnt(" #n ")" ::: "memory")
; template <class Epi, class Sched, bool ALIGN_EPI = false, bool SP2 = false>
; __device__ __forceinline__ void gemm_phase(PG8_LAS unsigned char* lds, const Gemm g, const Sched& S, const Epi& E, const int tid) {
;     ...
;             const bool last = (t == nt - 2);
;             const char* a1 = cA + (size_t)(t + 1) * kstep;
;             const char* a2 = last ? nA : cA + (size_t)(t + 2) * kstep; const char* b2 = last ? nB : cB + (size_t)(t + 2) * kstep;
;             const char* a3 = a2 + kstep; const char* b3 = b2 + kstep;
;             if (last && has_next) S.a_ready(nxt);
;             if constexpr (Epi::MID) { if (t == nt / 2) { PG8_SCHED; E.mid(acc, cur, wr, wc, fr, fq); PG8_SCHED; } }
;             if constexpr (SP2) {
;             PG8_LDB(B0, 0, 0); PG8_LDB(B1, 0, 1); PG8_SCHED; PG8_LDA(At, 0, 0); PG8_STAGE(PG8_SA(1, 1), a1 + hstep, voffA);
;             PG8_WAIT_V(8); PG8_WAIT_L(0); PG8_BAR; PG8_MMA(0, 0, At, B0); PG8_MMA(0, 1, At, B1); PG8_BAR; PG8_SCHED;
;             PG8_LDA(At, 0, 1); PG8_STAGE(PG8_SB(0, 0), b2, voffB); PG8_STAGE(PG8_SB(0, 1), b2 + hstep, voffB); PG8_STAGE(PG8_SA(0, 0), a2, voffA);
.LBB0_116:
	s_add_u32 s18, s44, s54
	s_addc_u32 s19, s45, s55
	s_add_u32 s18, s18, 0x100
	s_addc_u32 s19, s19, 0
	s_add_u32 s24, s60, s54
	s_addc_u32 s63, s61, s55
	s_cmpk_eq_i32 s54, 0x700
	s_cselect_b32 s35, s22, s19
	s_cselect_b32 s34, s49, s18
	s_cselect_b32 s19, s47, s63
	s_cselect_b32 s18, s59, s24
	s_add_i32 s24, 0, 0x10000
	v_add_u32_e32 v0, s24, v223
	s_add_i32 s63, 0, 0x14000
	ds_read_b128 v[132:135], v0
	ds_read_b128 v[136:139], v0 offset:1024
	ds_read_b128 v[140:143], v0 offset:2048
	ds_read_b128 v[144:147], v0 offset:3072
	v_add_u32_e32 v0, s63, v223
	ds_read_b128 v[148:151], v0
	ds_read_b128 v[152:155], v0 offset:1024
	ds_read_b128 v[156:159], v0 offset:2048
	ds_read_b128 v[160:163], v0 offset:3072
	v_lshl_add_u64 v[0:1], v[218:219], 0, s[54:55]
	s_add_i32 m0, s28, 0xc000
	ds_read_b128 v[164:167], v225
	ds_read_b128 v[168:171], v225 offset:1024
	ds_read_b128 v[172:175], v225 offset:2048
	ds_read_b128 v[176:179], v225 offset:3072
	ds_read_b128 v[180:183], v225 offset:4096
	ds_read_b128 v[184:187], v225 offset:5120
	ds_read_b128 v[188:191], v225 offset:6144
	ds_read_b128 v[192:195], v225 offset:7168
	global_load_lds_dwordx4 v[0:1], off
	v_lshl_add_u64 v[0:1], v[220:221], 0, s[54:55]
	s_add_i32 m0, s28, 0xe000
	s_nop 0
	global_load_lds_dwordx4 v[0:1], off
	s_waitcnt vmcnt(8)
	s_waitcnt lgkmcnt(0)
	s_setprio 1
	s_barrier
	v_mfma_f32_16x16x32_bf16 v[128:131], v[132:135], v[164:167], v[128:131]
	v_mfma_f32_16x16x32_bf16 v[124:127], v[140:143], v[164:167], v[124:127]
	v_mfma_f32_16x16x32_bf16 v[112:115], v[132:135], v[172:175], v[112:115]
	v_mfma_f32_16x16x32_bf16 v[108:111], v[140:143], v[172:175], v[108:111]
	v_mfma_f32_16x16x32_bf16 v[96:99], v[132:135], v[180:183], v[96:99]
	v_mfma_f32_16x16x32_bf16 v[92:95], v[140:143], v[180:183], v[92:95]
	v_mfma_f32_16x16x32_bf16 v[80:83], v[132:135], v[188:191], v[80:83]
	v_mfma_f32_16x16x32_bf16 v[76:79], v[140:143], v[188:191], v[76:79]
	v_mfma_f32_16x16x32_bf16 v[128:131], v[136:139], v[168:171], v[128:131]
	v_mfma_f32_16x16x32_bf16 v[124:127], v[144:147], v[168:171], v[124:127]
	v_mfma_f32_16x16x32_bf16 v[112:115], v[136:139], v[176:179], v[112:115]
	v_mfma_f32_16x16x32_bf16 v[108:111], v[144:147], v[176:179], v[108:111]
	v_mfma_f32_16x16x32_bf16 v[96:99], v[136:139], v[184:187], v[96:99]
	v_mfma_f32_16x16x32_bf16 v[92:95], v[144:147], v[184:187], v[92:95]
	v_mfma_f32_16x16x32_bf16 v[80:83], v[136:139], v[192:195], v[80:83]
	v_mfma_f32_16x16x32_bf16 v[76:79], v[144:147], v[192:195], v[76:79]
	s_setprio 0
	s_setprio 1
	v_mfma_f32_16x16x32_bf16 v[120:123], v[148:151], v[164:167], v[120:123]
	v_mfma_f32_16x16x32_bf16 v[116:119], v[156:159], v[164:167], v[116:119]
	v_mfma_f32_16x16x32_bf16 v[104:107], v[148:151], v[172:175], v[104:107]
	v_mfma_f32_16x16x32_bf16 v[100:103], v[156:159], v[172:175], v[100:103]
	v_mfma_f32_16x16x32_bf16 v[88:91], v[148:151], v[180:183], v[88:91]
	v_mfma_f32_16x16x32_bf16 v[84:87], v[156:159], v[180:183], v[84:87]
	v_mfma_f32_16x16x32_bf16 v[72:75], v[148:151], v[188:191], v[72:75]
	v_mfma_f32_16x16x32_bf16 v[68:71], v[156:159], v[188:191], v[68:71]
	v_mfma_f32_16x16x32_bf16 v[120:123], v[152:155], v[168:171], v[120:123]
	v_mfma_f32_16x16x32_bf16 v[116:119], v[160:163], v[168:171], v[116:119]
	v_mfma_f32_16x16x32_bf16 v[104:107], v[152:155], v[176:179], v[104:107]
	v_mfma_f32_16x16x32_bf16 v[100:103], v[160:163], v[176:179], v[100:103]
	v_mfma_f32_16x16x32_bf16 v[88:91], v[152:155], v[184:187], v[88:91]
	v_mfma_f32_16x16x32_bf16 v[84:87], v[160:163], v[184:187], v[84:87]
	v_mfma_f32_16x16x32_bf16 v[72:75], v[152:155], v[192:195], v[72:75]
	v_mfma_f32_16x16x32_bf16 v[68:71], v[160:163], v[192:195], v[68:71]
	s_barrier
	s_setprio 0
	s_add_i32 s24, s24, s3
	v_lshl_add_u64 v[0:1], s[18:19], 0, v[204:205]
	s_mov_b32 m0, s24
	ds_read_b128 v[164:167], v225 offset:16384
	ds_read_b128 v[168:171], v225 offset:17408
	ds_read_b128 v[172:175], v225 offset:18432
	ds_read_b128 v[176:179], v225 offset:19456
	ds_read_b128 v[180:183], v225 offset:20480
	ds_read_b128 v[184:187], v225 offset:21504
	ds_read_b128 v[188:191], v225 offset:22528
	ds_read_b128 v[192:195], v225 offset:23552
	global_load_lds_dwordx4 v[0:1], off
	s_add_i32 m0, s24, 0x2000
	s_add_u32 s64, s18, 0x40000
	v_lshl_add_u64 v[226:227], s[18:19], 0, v[208:209]
	s_addc_u32 s65, s19, 0
	s_add_i32 s24, s63, s3
	global_load_lds_dwordx4 v[226:227], off
	v_lshl_add_u64 v[228:229], s[64:65], 0, v[204:205]
	s_mov_b32 m0, s24
	v_lshl_add_u64 v[230:231], s[34:35], 0, v[206:207]
	global_load_lds_dwordx4 v[228:229], off
	v_lshl_add_u64 v[228:229], s[64:65], 0, v[208:209]
	s_add_i32 m0, s24, 0x2000
	s_nop 0
	global_load_lds_dwordx4 v[228:229], off
	v_lshl_add_u64 v[228:229], s[34:35], 0, v[202:203]
	s_mov_b32 m0, s28
	s_nop 0
	global_load_lds_dwordx4 v[228:229], off
	s_mov_b32 m0, s29
	s_nop 0
	global_load_lds_dwordx4 v[230:231], off
	s_waitcnt vmcnt(8)
	s_waitcnt lgkmcnt(0)
	s_setprio 1
	s_barrier
; #define PG8_STAGE(bufoff, gbase, voff) do { _Pragma("unroll") for (int _i = 0; _i < 2; ++_i) \
;         __builtin_amdgcn_global_load_lds((const unsigned*)((const char*)(gbase) + (voff)[_i]), (PG8_LAS unsigned*)(lds + (bufoff) + ldsw + _i * 8192), 16, 0, 0); } while (0)
; #define PG8_LDA(dst, b, h) do { _Pragma("unroll") for (int m = 0; m < 4; ++m) _Pragma("unroll") for (int k = 0; k < 2; ++k) dst[m][k] = *(const PG8_LAS bf16x8*)(lds + PG8_SA(b, h) + aoff + m * 2048 + k * 1024); } while (0)
; #define PG8_LDB(dst, b, h) do { _Pragma("unroll") for (int n = 0; n < 2; ++n) _Pragma("unroll") for (int k = 0; k < 2; ++k) dst[n][k] = *(const PG8_LAS bf16x8*)(lds + PG8_SB(b, h) + boff + n * 2048 + k * 1024); } while (0)
; #define PG8_MMA(ai, bj, At, Bt) do { __builtin_amdgcn_s_setprio(1); _Pragma("unroll") for (int m = 0; m < 4; ++m) _Pragma("unroll") for (int n = 0; n < 2; ++n) _Pragma("unroll") for (int k = 0; k < 2; ++k) \
;         acc[ai][bj][m][n] = __builtin_amdgcn_mfma_f32_16x16x32_bf16(Bt[n][k], At[m][k], acc[ai][bj][m][n], 0, 0, 0); __builtin_amdgcn_s_setprio(0); } while (0)
; #define PG8_WAIT_V(n) asm volatile("s_waitcnt vmcnt(" #n ")" ::: "memory")
; #define PG8_WAIT_L(n) asm volatile("s_waitcnt lgkmcnt(" #n ")" ::: "memory")
; #define PG8_BAR __builtin_amdgcn_s_barrier()
; #define PG8_SCHED __builtin_amdgcn_sched_barrier(0)
; template <class Epi, class Sched, bool ALIGN_EPI = false, bool SP2 = false>
; __device__ __forceinline__ void gemm_phase(PG8_LAS unsigned char* lds, const Gemm g, const Sched& S, const Epi& E, const int tid) {
;     ...
;             PG8_WAIT_V(8); PG8_WAIT_L(0); PG8_BAR; PG8_MMA(1, 0, At, B0); PG8_MMA(1, 1, At, B1); PG8_BAR; PG8_SCHED;
;             PG8_LDB(B0, 1, 0); PG8_LDB(B1, 1, 1); PG8_SCHED; PG8_LDA(At, 1, 0); PG8_STAGE(PG8_SA(0, 1), a2 + hstep, voffA);
;             PG8_WAIT_V(8); PG8_WAIT_L(0); PG8_BAR; PG8_MMA(0, 0, At, B0); PG8_MMA(0, 1, At, B1); PG8_BAR; PG8_SCHED;
	v_mfma_f32_16x16x32_bf16 v[64:67], v[132:135], v[164:167], v[64:67]
	v_mfma_f32_16x16x32_bf16 v[60:63], v[140:143], v[164:167], v[60:63]
	v_mfma_f32_16x16x32_bf16 v[48:51], v[132:135], v[172:175], v[48:51]
	v_mfma_f32_16x16x32_bf16 v[44:47], v[140:143], v[172:175], v[44:47]
	v_mfma_f32_16x16x32_bf16 v[32:35], v[132:135], v[180:183], v[32:35]
	v_mfma_f32_16x16x32_bf16 v[28:31], v[140:143], v[180:183], v[28:31]
	v_mfma_f32_16x16x32_bf16 v[16:19], v[132:135], v[188:191], v[16:19]
	v_mfma_f32_16x16x32_bf16 v[12:15], v[140:143], v[188:191], v[12:15]
	v_mfma_f32_16x16x32_bf16 v[64:67], v[136:139], v[168:171], v[64:67]
	v_mfma_f32_16x16x32_bf16 v[60:63], v[144:147], v[168:171], v[60:63]
	v_mfma_f32_16x16x32_bf16 v[48:51], v[136:139], v[176:179], v[48:51]
	v_mfma_f32_16x16x32_bf16 v[44:47], v[144:147], v[176:179], v[44:47]
	v_mfma_f32_16x16x32_bf16 v[32:35], v[136:139], v[184:187], v[32:35]
	v_mfma_f32_16x16x32_bf16 v[28:31], v[144:147], v[184:187], v[28:31]
	v_mfma_f32_16x16x32_bf16 v[16:19], v[136:139], v[192:195], v[16:19]
	v_mfma_f32_16x16x32_bf16 v[12:15], v[144:147], v[192:195], v[12:15]
	s_setprio 0
	s_setprio 1
	v_mfma_f32_16x16x32_bf16 v[56:59], v[148:151], v[164:167], v[56:59]
	v_mfma_f32_16x16x32_bf16 v[52:55], v[156:159], v[164:167], v[52:55]
	v_mfma_f32_16x16x32_bf16 v[40:43], v[148:151], v[172:175], v[40:43]
	v_mfma_f32_16x16x32_bf16 v[36:39], v[156:159], v[172:175], v[36:39]
	v_mfma_f32_16x16x32_bf16 v[24:27], v[148:151], v[180:183], v[24:27]
	v_mfma_f32_16x16x32_bf16 v[20:23], v[156:159], v[180:183], v[20:23]
	v_mfma_f32_16x16x32_bf16 v[8:11], v[148:151], v[188:191], v[8:11]
	v_mfma_f32_16x16x32_bf16 v[4:7], v[156:159], v[188:191], v[4:7]
	v_mfma_f32_16x16x32_bf16 v[56:59], v[152:155], v[168:171], v[56:59]
	v_mfma_f32_16x16x32_bf16 v[52:55], v[160:163], v[168:171], v[52:55]
	v_mfma_f32_16x16x32_bf16 v[40:43], v[152:155], v[176:179], v[40:43]
	v_mfma_f32_16x16x32_bf16 v[36:39], v[160:163], v[176:179], v[36:39]
	v_mfma_f32_16x16x32_bf16 v[24:27], v[152:155], v[184:187], v[24:27]
	v_mfma_f32_16x16x32_bf16 v[20:23], v[160:163], v[184:187], v[20:23]
	v_mfma_f32_16x16x32_bf16 v[8:11], v[152:155], v[192:195], v[8:11]
	v_mfma_f32_16x16x32_bf16 v[4:7], v[160:163], v[192:195], v[4:7]
	s_barrier
	s_setprio 0
	s_add_i32 s24, 0, 0x18000
	v_add_u32_e32 v3, s24, v223
	s_add_i32 s63, 0, 0x1c000
	ds_read_b128 v[132:135], v3
	ds_read_b128 v[136:139], v3 offset:1024
	ds_read_b128 v[140:143], v3 offset:2048
	ds_read_b128 v[144:147], v3 offset:3072
	v_add_u32_e32 v3, s63, v223
	ds_read_b128 v[148:151], v3
	ds_read_b128 v[152:155], v3 offset:1024
	ds_read_b128 v[156:159], v3 offset:2048
	ds_read_b128 v[160:163], v3 offset:3072
	s_add_u32 s34, s34, 0x40000
	s_addc_u32 s35, s35, 0
	s_mov_b32 m0, s30
	v_lshl_add_u64 v[232:233], s[34:35], 0, v[202:203]
	ds_read_b128 v[164:167], v225 offset:32768
	ds_read_b128 v[168:171], v225 offset:33792
	ds_read_b128 v[172:175], v225 offset:34816
	ds_read_b128 v[176:179], v225 offset:35840
	ds_read_b128 v[180:183], v225 offset:36864
	ds_read_b128 v[184:187], v225 offset:37888
	ds_read_b128 v[188:191], v225 offset:38912
	ds_read_b128 v[192:195], v225 offset:39936
	global_load_lds_dwordx4 v[232:233], off
	v_lshl_add_u64 v[232:233], s[34:35], 0, v[206:207]
	s_mov_b32 m0, s31
	s_nop 0
	global_load_lds_dwordx4 v[232:233], off
	s_waitcnt vmcnt(8)
	s_waitcnt lgkmcnt(0)
	s_setprio 1
	s_barrier
	v_mfma_f32_16x16x32_bf16 v[128:131], v[132:135], v[164:167], v[128:131]
	v_mfma_f32_16x16x32_bf16 v[124:127], v[140:143], v[164:167], v[124:127]
	v_mfma_f32_16x16x32_bf16 v[112:115], v[132:135], v[172:175], v[112:115]
	v_mfma_f32_16x16x32_bf16 v[108:111], v[140:143], v[172:175], v[108:111]
	v_mfma_f32_16x16x32_bf16 v[96:99], v[132:135], v[180:183], v[96:99]
	v_mfma_f32_16x16x32_bf16 v[92:95], v[140:143], v[180:183], v[92:95]
	v_mfma_f32_16x16x32_bf16 v[80:83], v[132:135], v[188:191], v[80:83]
	v_mfma_f32_16x16x32_bf16 v[76:79], v[140:143], v[188:191], v[76:79]
	v_mfma_f32_16x16x32_bf16 v[128:131], v[136:139], v[168:171], v[128:131]
	v_mfma_f32_16x16x32_bf16 v[124:127], v[144:147], v[168:171], v[124:127]
	v_mfma_f32_16x16x32_bf16 v[112:115], v[136:139], v[176:179], v[112:115]
	v_mfma_f32_16x16x32_bf16 v[108:111], v[144:147], v[176:179], v[108:111]
	v_mfma_f32_16x16x32_bf16 v[96:99], v[136:139], v[184:187], v[96:99]
	v_mfma_f32_16x16x32_bf16 v[92:95], v[144:147], v[184:187], v[92:95]
	v_mfma_f32_16x16x32_bf16 v[80:83], v[136:139], v[192:195], v[80:83]
	v_mfma_f32_16x16x32_bf16 v[76:79], v[144:147], v[192:195], v[76:79]
	s_setprio 0
	s_setprio 1
	v_mfma_f32_16x16x32_bf16 v[120:123], v[148:151], v[164:167], v[120:123]
	v_mfma_f32_16x16x32_bf16 v[116:119], v[156:159], v[164:167], v[116:119]
	v_mfma_f32_16x16x32_bf16 v[104:107], v[148:151], v[172:175], v[104:107]
	v_mfma_f32_16x16x32_bf16 v[100:103], v[156:159], v[172:175], v[100:103]
	v_mfma_f32_16x16x32_bf16 v[88:91], v[148:151], v[180:183], v[88:91]
	v_mfma_f32_16x16x32_bf16 v[84:87], v[156:159], v[180:183], v[84:87]
	v_mfma_f32_16x16x32_bf16 v[72:75], v[148:151], v[188:191], v[72:75]
	v_mfma_f32_16x16x32_bf16 v[68:71], v[156:159], v[188:191], v[68:71]
	v_mfma_f32_16x16x32_bf16 v[120:123], v[152:155], v[168:171], v[120:123]
	v_mfma_f32_16x16x32_bf16 v[116:119], v[160:163], v[168:171], v[116:119]
	v_mfma_f32_16x16x32_bf16 v[104:107], v[152:155], v[176:179], v[104:107]
	v_mfma_f32_16x16x32_bf16 v[100:103], v[160:163], v[176:179], v[100:103]
	v_mfma_f32_16x16x32_bf16 v[88:91], v[152:155], v[184:187], v[88:91]
	v_mfma_f32_16x16x32_bf16 v[84:87], v[160:163], v[184:187], v[84:87]
	v_mfma_f32_16x16x32_bf16 v[72:75], v[152:155], v[192:195], v[72:75]
	v_mfma_f32_16x16x32_bf16 v[68:71], v[160:163], v[192:195], v[68:71]
	s_barrier
; #define PG8_STAGE(bufoff, gbase, voff) do { _Pragma("unroll") for (int _i = 0; _i < 2; ++_i) \
;         __builtin_amdgcn_global_load_lds((const unsigned*)((const char*)(gbase) + (voff)[_i]), (PG8_LAS unsigned*)(lds + (bufoff) + ldsw + _i * 8192), 16, 0, 0); } while (0)
; #define PG8_LDA(dst, b, h) do { _Pragma("unroll") for (int m = 0; m < 4; ++m) _Pragma("unroll") for (int k = 0; k < 2; ++k) dst[m][k] = *(const PG8_LAS bf16x8*)(lds + PG8_SA(b, h) + aoff + m * 2048 + k * 1024); } while (0)
; #define PG8_MMA(ai, bj, At, Bt) do { __builtin_amdgcn_s_setprio(1); _Pragma("unroll") for (int m = 0; m < 4; ++m) _Pragma("unroll") for (int n = 0; n < 2; ++n) _Pragma("unroll") for (int k = 0; k < 2; ++k) \
;         acc[ai][bj][m][n] = __builtin_amdgcn_mfma_f32_16x16x32_bf16(Bt[n][k], At[m][k], acc[ai][bj][m][n], 0, 0, 0); __builtin_amdgcn_s_setprio(0); } while (0)
; #define PG8_WAIT_V(n) asm volatile("s_waitcnt vmcnt(" #n ")" ::: "memory")
; #define PG8_WAIT_L(n) asm volatile("s_waitcnt lgkmcnt(" #n ")" ::: "memory")
; #define PG8_BAR __builtin_amdgcn_s_barrier()
; #define PG8_SCHED __builtin_amdgcn_sched_barrier(0)
; template <class Epi, class Sched, bool ALIGN_EPI = false, bool SP2 = false>
; __device__ __forceinline__ void gemm_phase(PG8_LAS unsigned char* lds, const Gemm g, const Sched& S, const Epi& E, const int tid) {
;     ...
;             PG8_LDA(At, 1, 1); PG8_STAGE(PG8_SB(1, 0), b3, voffB); PG8_STAGE(PG8_SB(1, 1), b3 + hstep, voffB); PG8_STAGE(PG8_SA(1, 0), a3, voffA);
;             PG8_WAIT_V(8); PG8_WAIT_L(0); PG8_BAR; PG8_MMA(1, 0, At, B0); PG8_MMA(1, 1, At, B1); PG8_BAR; PG8_SCHED;
	s_setprio 0
	s_add_i32 s24, s24, s3
	v_lshl_add_u64 v[0:1], v[0:1], 0, s[66:67]
	s_mov_b32 m0, s24
	ds_read_b128 v[164:167], v225 offset:49152
	ds_read_b128 v[168:171], v225 offset:50176
	ds_read_b128 v[172:175], v225 offset:51200
	ds_read_b128 v[176:179], v225 offset:52224
	ds_read_b128 v[180:183], v225 offset:53248
	ds_read_b128 v[184:187], v225 offset:54272
	ds_read_b128 v[188:191], v225 offset:55296
	ds_read_b128 v[192:195], v225 offset:56320
	global_load_lds_dwordx4 v[0:1], off
	s_add_i32 m0, s24, 0x2000
	s_add_u32 s18, s18, 0x40080
	v_lshl_add_u64 v[0:1], v[226:227], 0, s[66:67]
	s_addc_u32 s19, s19, 0
	s_add_i32 s24, s63, s3
	global_load_lds_dwordx4 v[0:1], off
	v_lshl_add_u64 v[0:1], s[18:19], 0, v[204:205]
	s_mov_b32 m0, s24
	s_nop 0
	global_load_lds_dwordx4 v[0:1], off
	v_lshl_add_u64 v[0:1], s[18:19], 0, v[208:209]
	s_add_i32 m0, s24, 0x2000
	s_nop 0
	global_load_lds_dwordx4 v[0:1], off
	v_lshl_add_u64 v[0:1], v[228:229], 0, s[66:67]
	s_mov_b32 m0, s56
	s_nop 0
	global_load_lds_dwordx4 v[0:1], off
	v_lshl_add_u64 v[0:1], v[230:231], 0, s[66:67]
	s_mov_b32 m0, s57
	s_nop 0
	global_load_lds_dwordx4 v[0:1], off
	s_waitcnt vmcnt(8)
	s_waitcnt lgkmcnt(0)
	s_setprio 1
	s_barrier
	v_mfma_f32_16x16x32_bf16 v[64:67], v[132:135], v[164:167], v[64:67]
	v_mfma_f32_16x16x32_bf16 v[60:63], v[140:143], v[164:167], v[60:63]
	v_mfma_f32_16x16x32_bf16 v[48:51], v[132:135], v[172:175], v[48:51]
	v_mfma_f32_16x16x32_bf16 v[44:47], v[140:143], v[172:175], v[44:47]
	v_mfma_f32_16x16x32_bf16 v[32:35], v[132:135], v[180:183], v[32:35]
	v_mfma_f32_16x16x32_bf16 v[28:31], v[140:143], v[180:183], v[28:31]
	v_mfma_f32_16x16x32_bf16 v[16:19], v[132:135], v[188:191], v[16:19]
	v_mfma_f32_16x16x32_bf16 v[12:15], v[140:143], v[188:191], v[12:15]
	v_mfma_f32_16x16x32_bf16 v[64:67], v[136:139], v[168:171], v[64:67]
	v_mfma_f32_16x16x32_bf16 v[60:63], v[144:147], v[168:171], v[60:63]
	v_mfma_f32_16x16x32_bf16 v[48:51], v[136:139], v[176:179], v[48:51]
	v_mfma_f32_16x16x32_bf16 v[44:47], v[144:147], v[176:179], v[44:47]
	v_mfma_f32_16x16x32_bf16 v[32:35], v[136:139], v[184:187], v[32:35]
	v_mfma_f32_16x16x32_bf16 v[28:31], v[144:147], v[184:187], v[28:31]
	v_mfma_f32_16x16x32_bf16 v[16:19], v[136:139], v[192:195], v[16:19]
	v_mfma_f32_16x16x32_bf16 v[12:15], v[144:147], v[192:195], v[12:15]
	s_setprio 0
	s_setprio 1
	v_mfma_f32_16x16x32_bf16 v[56:59], v[148:151], v[164:167], v[56:59]
	v_mfma_f32_16x16x32_bf16 v[52:55], v[156:159], v[164:167], v[52:55]
	v_mfma_f32_16x16x32_bf16 v[40:43], v[148:151], v[172:175], v[40:43]
	v_mfma_f32_16x16x32_bf16 v[36:39], v[156:159], v[172:175], v[36:39]
	v_mfma_f32_16x16x32_bf16 v[24:27], v[148:151], v[180:183], v[24:27]
	v_mfma_f32_16x16x32_bf16 v[20:23], v[156:159], v[180:183], v[20:23]
	v_mfma_f32_16x16x32_bf16 v[8:11], v[148:151], v[188:191], v[8:11]
	v_mfma_f32_16x16x32_bf16 v[4:7], v[156:159], v[188:191], v[4:7]
	v_mfma_f32_16x16x32_bf16 v[56:59], v[152:155], v[168:171], v[56:59]
	v_mfma_f32_16x16x32_bf16 v[52:55], v[160:163], v[168:171], v[52:55]
	v_mfma_f32_16x16x32_bf16 v[40:43], v[152:155], v[176:179], v[40:43]
	v_mfma_f32_16x16x32_bf16 v[36:39], v[160:163], v[176:179], v[36:39]
	v_mfma_f32_16x16x32_bf16 v[24:27], v[152:155], v[184:187], v[24:27]
	v_mfma_f32_16x16x32_bf16 v[20:23], v[160:163], v[184:187], v[20:23]
	v_mfma_f32_16x16x32_bf16 v[8:11], v[152:155], v[192:195], v[8:11]
	v_mfma_f32_16x16x32_bf16 v[4:7], v[160:163], v[192:195], v[4:7]
	s_barrier
	s_setprio 0
	s_add_i32 s62, s62, 2
	s_add_u32 s54, s54, 0x100
	s_addc_u32 s55, s55, 0
	s_cmp_gt_u32 s62, 13
	s_cbranch_scc1 .LBB0_119

; #define PG8_STAGE(bufoff, gbase, voff) do { _Pragma("unroll") for (int _i = 0; _i < 2; ++_i) \
;         __builtin_amdgcn_global_load_lds((const unsigned*)((const char*)(gbase) + (voff)[_i]), (PG8_LAS unsigned*)(lds + (bufoff) + ldsw + _i * 8192), 16, 0, 0); } while (0)
; #define PG8_LDA(dst, b, h) do { _Pragma("unroll") for (int m = 0; m < 4; ++m) _Pragma("unroll") for (int k = 0; k < 2; ++k) dst[m][k] = *(const PG8_LAS bf16x8*)(lds + PG8_SA(b, h) + aoff + m * 2048 + k * 1024); } while (0)
; #define PG8_LDB(dst, b, h) do { _Pragma("unroll") for (int n = 0; n < 2; ++n) _Pragma("unroll") for (int k = 0; k < 2; ++k) dst[n][k] = *(const PG8_LAS bf16x8*)(lds + PG8_SB(b, h) + boff + n * 2048 + k * 1024); } while (0)
; #define PG8_MMA(ai, bj, At, Bt) do { __builtin_amdgcn_s_setprio(1); _Pragma("unroll") for (int m = 0; m < 4; ++m) _Pragma("unroll") for (int n = 0; n < 2; ++n) _Pragma("unroll") for (int k = 0; k < 2; ++k) \
;         acc[ai][bj][m][n] = __builtin_amdgcn_mfma_f32_16x16x32_bf16(Bt[n][k], At[m][k], acc[ai][bj][m][n], 0, 0, 0); __builtin_amdgcn_s_setprio(0); } while (0)
; #define PG8_WAIT_V(n) asm volatile("s_waitcnt vmcnt(" #n ")" ::: "memory")
; #define PG8_WAIT_L(n) asm volatile("s_waitcnt lgkmcnt(" #n ")" ::: "memory")
; template <class Epi, class Sched, bool ALIGN_EPI = false, bool SP2 = false>
; __device__ __forceinline__ void gemm_phase(PG8_LAS unsigned char* lds, const Gemm g, const Sched& S, const Epi& E, const int tid) {
;     ...
;             const bool last = (t == nt - 2);
;             const char* a1 = cA + (size_t)(t + 1) * kstep;
;             const char* a2 = last ? nA : cA + (size_t)(t + 2) * kstep; const char* b2 = last ? nB : cB + (size_t)(t + 2) * kstep;
;             const char* a3 = a2 + kstep; const char* b3 = b2 + kstep;
;             if (last && has_next) S.a_ready(nxt);
;             if constexpr (Epi::MID) { if (t == nt / 2) { PG8_SCHED; E.mid(acc, cur, wr, wc, fr, fq); PG8_SCHED; } }
;             if constexpr (SP2) {
;             PG8_LDB(B0, 0, 0); PG8_LDB(B1, 0, 1); PG8_SCHED; PG8_LDA(At, 0, 0); PG8_STAGE(PG8_SA(1, 1), a1 + hstep, voffA);
;             PG8_WAIT_V(8); PG8_WAIT_L(0); PG8_BAR; PG8_MMA(0, 0, At, B0); PG8_MMA(0, 1, At, B1); PG8_BAR; PG8_SCHED;
;             PG8_LDA(At, 0, 1); PG8_STAGE(PG8_SB(0, 0), b2, voffB); PG8_STAGE(PG8_SB(0, 1), b2 + hstep, voffB); PG8_STAGE(PG8_SA(0, 0), a2, voffA);
.LBB0_172:
	s_add_u32 s42, s18, 0x100
	s_addc_u32 s43, s19, 0
	s_add_i32 s86, 0, 0x10000
	s_cmp_eq_u32 s85, 40
	s_cselect_b32 s45, s57, s43
	s_cselect_b32 s44, s56, s42
	s_cselect_b32 s35, s59, s84
	s_cselect_b32 s34, s58, s65
	s_add_i32 s87, 0, 0x14000
	v_add_u32_e32 v144, s86, v186
	v_add_u32_e32 v170, s87, v186
	ds_read_b128 v[124:127], v144
	ds_read_b128 v[136:139], v144 offset:1024
	ds_read_b128 v[140:143], v144 offset:2048
	ds_read_b128 v[144:147], v144 offset:3072
	ds_read_b128 v[148:151], v170
	ds_read_b128 v[152:155], v170 offset:1024
	ds_read_b128 v[156:159], v170 offset:2048
	ds_read_b128 v[170:173], v170 offset:3072
	v_lshl_add_u64 v[194:195], s[18:19], 0, v[166:167]
	s_add_i32 m0, s24, 0xc000
	ds_read_b128 v[174:177], v188
	ds_read_b128 v[178:181], v188 offset:1024
	ds_read_b128 v[182:185], v188 offset:2048
	ds_read_b128 v[190:193], v188 offset:3072
	ds_read_b128 v[202:205], v188 offset:4096
	ds_read_b128 v[206:209], v188 offset:5120
	ds_read_b128 v[210:213], v188 offset:6144
	ds_read_b128 v[214:217], v188 offset:7168
	global_load_lds_dwordx4 v[194:195], off
	v_lshl_add_u64 v[194:195], s[18:19], 0, v[168:169]
	s_add_i32 m0, s24, 0xe000
	s_nop 0
	global_load_lds_dwordx4 v[194:195], off
	s_waitcnt vmcnt(8)
	s_waitcnt lgkmcnt(0)
	s_setprio 1
	s_barrier
	v_mfma_f32_16x16x32_bf16 v[132:135], v[124:127], v[174:177], v[132:135]
	v_mfma_f32_16x16x32_bf16 v[128:131], v[140:143], v[174:177], v[128:131]
	v_mfma_f32_16x16x32_bf16 v[112:115], v[124:127], v[182:185], v[112:115]
	v_mfma_f32_16x16x32_bf16 v[108:111], v[140:143], v[182:185], v[108:111]
	v_mfma_f32_16x16x32_bf16 v[96:99], v[124:127], v[202:205], v[96:99]
	v_mfma_f32_16x16x32_bf16 v[92:95], v[140:143], v[202:205], v[92:95]
	v_mfma_f32_16x16x32_bf16 v[80:83], v[124:127], v[210:213], v[80:83]
	v_mfma_f32_16x16x32_bf16 v[76:79], v[140:143], v[210:213], v[76:79]
	v_mfma_f32_16x16x32_bf16 v[132:135], v[136:139], v[178:181], v[132:135]
	v_mfma_f32_16x16x32_bf16 v[128:131], v[144:147], v[178:181], v[128:131]
	v_mfma_f32_16x16x32_bf16 v[112:115], v[136:139], v[190:193], v[112:115]
	v_mfma_f32_16x16x32_bf16 v[108:111], v[144:147], v[190:193], v[108:111]
	v_mfma_f32_16x16x32_bf16 v[96:99], v[136:139], v[206:209], v[96:99]
	v_mfma_f32_16x16x32_bf16 v[92:95], v[144:147], v[206:209], v[92:95]
	v_mfma_f32_16x16x32_bf16 v[80:83], v[136:139], v[214:217], v[80:83]
	v_mfma_f32_16x16x32_bf16 v[76:79], v[144:147], v[214:217], v[76:79]
	s_setprio 0
	s_setprio 1
	v_mfma_f32_16x16x32_bf16 v[120:123], v[148:151], v[174:177], v[120:123]
	v_mfma_f32_16x16x32_bf16 v[116:119], v[156:159], v[174:177], v[116:119]
	v_mfma_f32_16x16x32_bf16 v[104:107], v[148:151], v[182:185], v[104:107]
	v_mfma_f32_16x16x32_bf16 v[100:103], v[156:159], v[182:185], v[100:103]
	v_mfma_f32_16x16x32_bf16 v[88:91], v[148:151], v[202:205], v[88:91]
	v_mfma_f32_16x16x32_bf16 v[84:87], v[156:159], v[202:205], v[84:87]
	v_mfma_f32_16x16x32_bf16 v[72:75], v[148:151], v[210:213], v[72:75]
	v_mfma_f32_16x16x32_bf16 v[68:71], v[156:159], v[210:213], v[68:71]
	v_mfma_f32_16x16x32_bf16 v[120:123], v[152:155], v[178:181], v[120:123]
	v_mfma_f32_16x16x32_bf16 v[116:119], v[170:173], v[178:181], v[116:119]
	v_mfma_f32_16x16x32_bf16 v[104:107], v[152:155], v[190:193], v[104:107]
	v_mfma_f32_16x16x32_bf16 v[100:103], v[170:173], v[190:193], v[100:103]
	v_mfma_f32_16x16x32_bf16 v[88:91], v[152:155], v[206:209], v[88:91]
	v_mfma_f32_16x16x32_bf16 v[84:87], v[170:173], v[206:209], v[84:87]
	v_mfma_f32_16x16x32_bf16 v[72:75], v[152:155], v[214:217], v[72:75]
	v_mfma_f32_16x16x32_bf16 v[68:71], v[170:173], v[214:217], v[68:71]
	s_barrier
	s_setprio 0
	s_add_i32 s18, s86, s2
	v_lshl_add_u64 v[194:195], s[34:35], 0, v[160:161]
	s_mov_b32 m0, s18
	ds_read_b128 v[174:177], v188 offset:16384
	ds_read_b128 v[178:181], v188 offset:17408
	ds_read_b128 v[182:185], v188 offset:18432
	ds_read_b128 v[190:193], v188 offset:19456
	ds_read_b128 v[202:205], v188 offset:20480
	ds_read_b128 v[206:209], v188 offset:21504
	ds_read_b128 v[210:213], v188 offset:22528
	ds_read_b128 v[214:217], v188 offset:23552
	global_load_lds_dwordx4 v[194:195], off
	s_add_i32 m0, s18, 0x2000
	s_add_u32 s18, s34, 0xb0000
	v_lshl_add_u64 v[218:219], s[34:35], 0, v[164:165]
	s_addc_u32 s19, s35, 0
	s_add_i32 s86, s87, s2
	global_load_lds_dwordx4 v[218:219], off
	v_lshl_add_u64 v[220:221], s[18:19], 0, v[160:161]
	s_mov_b32 m0, s86
	v_lshl_add_u64 v[222:223], s[44:45], 0, v[162:163]
	global_load_lds_dwordx4 v[220:221], off
	v_lshl_add_u64 v[220:221], s[18:19], 0, v[164:165]
	s_add_i32 m0, s86, 0x2000
	s_nop 0
	global_load_lds_dwordx4 v[220:221], off
	v_lshl_add_u64 v[220:221], s[44:45], 0, v[0:1]
	s_mov_b32 m0, s24
	s_nop 0
	global_load_lds_dwordx4 v[220:221], off
	s_mov_b32 m0, s25
	s_nop 0
	global_load_lds_dwordx4 v[222:223], off
	s_waitcnt vmcnt(8)
	s_waitcnt lgkmcnt(0)
	s_setprio 1
	s_barrier
; #define PG8_STAGE(bufoff, gbase, voff) do { _Pragma("unroll") for (int _i = 0; _i < 2; ++_i) \
;         __builtin_amdgcn_global_load_lds((const unsigned*)((const char*)(gbase) + (voff)[_i]), (PG8_LAS unsigned*)(lds + (bufoff) + ldsw + _i * 8192), 16, 0, 0); } while (0)
; #define PG8_LDA(dst, b, h) do { _Pragma("unroll") for (int m = 0; m < 4; ++m) _Pragma("unroll") for (int k = 0; k < 2; ++k) dst[m][k] = *(const PG8_LAS bf16x8*)(lds + PG8_SA(b, h) + aoff + m * 2048 + k * 1024); } while (0)
; #define PG8_LDB(dst, b, h) do { _Pragma("unroll") for (int n = 0; n < 2; ++n) _Pragma("unroll") for (int k = 0; k < 2; ++k) dst[n][k] = *(const PG8_LAS bf16x8*)(lds + PG8_SB(b, h) + boff + n * 2048 + k * 1024); } while (0)
; #define PG8_MMA(ai, bj, At, Bt) do { __builtin_amdgcn_s_setprio(1); _Pragma("unroll") for (int m = 0; m < 4; ++m) _Pragma("unroll") for (int n = 0; n < 2; ++n) _Pragma("unroll") for (int k = 0; k < 2; ++k) \
;         acc[ai][bj][m][n] = __builtin_amdgcn_mfma_f32_16x16x32_bf16(Bt[n][k], At[m][k], acc[ai][bj][m][n], 0, 0, 0); __builtin_amdgcn_s_setprio(0); } while (0)
; #define PG8_WAIT_V(n) asm volatile("s_waitcnt vmcnt(" #n ")" ::: "memory")
; #define PG8_WAIT_L(n) asm volatile("s_waitcnt lgkmcnt(" #n ")" ::: "memory")
; #define PG8_BAR __builtin_amdgcn_s_barrier()
; #define PG8_SCHED __builtin_amdgcn_sched_barrier(0)
; template <class Epi, class Sched, bool ALIGN_EPI = false, bool SP2 = false>
; __device__ __forceinline__ void gemm_phase(PG8_LAS unsigned char* lds, const Gemm g, const Sched& S, const Epi& E, const int tid) {
;     ...
;             PG8_WAIT_V(8); PG8_WAIT_L(0); PG8_BAR; PG8_MMA(1, 0, At, B0); PG8_MMA(1, 1, At, B1); PG8_BAR; PG8_SCHED;
;             PG8_LDB(B0, 1, 0); PG8_LDB(B1, 1, 1); PG8_SCHED; PG8_LDA(At, 1, 0); PG8_STAGE(PG8_SA(0, 1), a2 + hstep, voffA);
;             PG8_WAIT_V(8); PG8_WAIT_L(0); PG8_BAR; PG8_MMA(0, 0, At, B0); PG8_MMA(0, 1, At, B1); PG8_BAR; PG8_SCHED;
	v_mfma_f32_16x16x32_bf16 v[64:67], v[124:127], v[174:177], v[64:67]
	v_mfma_f32_16x16x32_bf16 v[60:63], v[140:143], v[174:177], v[60:63]
	v_mfma_f32_16x16x32_bf16 v[48:51], v[124:127], v[182:185], v[48:51]
	v_mfma_f32_16x16x32_bf16 v[44:47], v[140:143], v[182:185], v[44:47]
	v_mfma_f32_16x16x32_bf16 v[32:35], v[124:127], v[202:205], v[32:35]
	v_mfma_f32_16x16x32_bf16 v[28:31], v[140:143], v[202:205], v[28:31]
	v_mfma_f32_16x16x32_bf16 v[16:19], v[124:127], v[210:213], v[16:19]
	v_mfma_f32_16x16x32_bf16 v[12:15], v[140:143], v[210:213], v[12:15]
	v_mfma_f32_16x16x32_bf16 v[64:67], v[136:139], v[178:181], v[64:67]
	v_mfma_f32_16x16x32_bf16 v[60:63], v[144:147], v[178:181], v[60:63]
	v_mfma_f32_16x16x32_bf16 v[48:51], v[136:139], v[190:193], v[48:51]
	v_mfma_f32_16x16x32_bf16 v[44:47], v[144:147], v[190:193], v[44:47]
	v_mfma_f32_16x16x32_bf16 v[32:35], v[136:139], v[206:209], v[32:35]
	v_mfma_f32_16x16x32_bf16 v[28:31], v[144:147], v[206:209], v[28:31]
	v_mfma_f32_16x16x32_bf16 v[16:19], v[136:139], v[214:217], v[16:19]
	v_mfma_f32_16x16x32_bf16 v[12:15], v[144:147], v[214:217], v[12:15]
	s_setprio 0
	s_setprio 1
	v_mfma_f32_16x16x32_bf16 v[56:59], v[148:151], v[174:177], v[56:59]
	v_mfma_f32_16x16x32_bf16 v[52:55], v[156:159], v[174:177], v[52:55]
	v_mfma_f32_16x16x32_bf16 v[40:43], v[148:151], v[182:185], v[40:43]
	v_mfma_f32_16x16x32_bf16 v[36:39], v[156:159], v[182:185], v[36:39]
	v_mfma_f32_16x16x32_bf16 v[24:27], v[148:151], v[202:205], v[24:27]
	v_mfma_f32_16x16x32_bf16 v[20:23], v[156:159], v[202:205], v[20:23]
	v_mfma_f32_16x16x32_bf16 v[8:11], v[148:151], v[210:213], v[8:11]
	v_mfma_f32_16x16x32_bf16 v[4:7], v[156:159], v[210:213], v[4:7]
	v_mfma_f32_16x16x32_bf16 v[56:59], v[152:155], v[178:181], v[56:59]
	v_mfma_f32_16x16x32_bf16 v[52:55], v[170:173], v[178:181], v[52:55]
	v_mfma_f32_16x16x32_bf16 v[40:43], v[152:155], v[190:193], v[40:43]
	v_mfma_f32_16x16x32_bf16 v[36:39], v[170:173], v[190:193], v[36:39]
	v_mfma_f32_16x16x32_bf16 v[24:27], v[152:155], v[206:209], v[24:27]
	v_mfma_f32_16x16x32_bf16 v[20:23], v[170:173], v[206:209], v[20:23]
	v_mfma_f32_16x16x32_bf16 v[8:11], v[152:155], v[214:217], v[8:11]
	v_mfma_f32_16x16x32_bf16 v[4:7], v[170:173], v[214:217], v[4:7]
	s_barrier
	s_setprio 0
	s_add_i32 s86, 0, 0x18000
	s_add_i32 s87, 0, 0x1c000
	v_add_u32_e32 v144, s86, v186
	v_add_u32_e32 v170, s87, v186
	ds_read_b128 v[124:127], v144
	ds_read_b128 v[136:139], v144 offset:1024
	ds_read_b128 v[140:143], v144 offset:2048
	ds_read_b128 v[144:147], v144 offset:3072
	ds_read_b128 v[148:151], v170
	ds_read_b128 v[152:155], v170 offset:1024
	ds_read_b128 v[156:159], v170 offset:2048
	ds_read_b128 v[170:173], v170 offset:3072
	s_add_u32 s18, s44, 0xb0000
	s_addc_u32 s19, s45, 0
	s_mov_b32 m0, s28
	v_lshl_add_u64 v[224:225], s[18:19], 0, v[0:1]
	ds_read_b128 v[174:177], v188 offset:32768
	ds_read_b128 v[178:181], v188 offset:33792
	ds_read_b128 v[182:185], v188 offset:34816
	ds_read_b128 v[190:193], v188 offset:35840
	ds_read_b128 v[202:205], v188 offset:36864
	ds_read_b128 v[206:209], v188 offset:37888
	ds_read_b128 v[210:213], v188 offset:38912
	ds_read_b128 v[214:217], v188 offset:39936
	global_load_lds_dwordx4 v[224:225], off
	v_lshl_add_u64 v[224:225], s[18:19], 0, v[162:163]
	s_mov_b32 m0, s29
	s_nop 0
	global_load_lds_dwordx4 v[224:225], off
	s_waitcnt vmcnt(8)
	s_waitcnt lgkmcnt(0)
	s_setprio 1
	s_barrier
	v_mfma_f32_16x16x32_bf16 v[132:135], v[124:127], v[174:177], v[132:135]
	v_mfma_f32_16x16x32_bf16 v[128:131], v[140:143], v[174:177], v[128:131]
	v_mfma_f32_16x16x32_bf16 v[112:115], v[124:127], v[182:185], v[112:115]
	v_mfma_f32_16x16x32_bf16 v[108:111], v[140:143], v[182:185], v[108:111]
	v_mfma_f32_16x16x32_bf16 v[96:99], v[124:127], v[202:205], v[96:99]
	v_mfma_f32_16x16x32_bf16 v[92:95], v[140:143], v[202:205], v[92:95]
	v_mfma_f32_16x16x32_bf16 v[80:83], v[124:127], v[210:213], v[80:83]
	v_mfma_f32_16x16x32_bf16 v[76:79], v[140:143], v[210:213], v[76:79]
	v_mfma_f32_16x16x32_bf16 v[132:135], v[136:139], v[178:181], v[132:135]
	v_mfma_f32_16x16x32_bf16 v[128:131], v[144:147], v[178:181], v[128:131]
	v_mfma_f32_16x16x32_bf16 v[112:115], v[136:139], v[190:193], v[112:115]
	v_mfma_f32_16x16x32_bf16 v[108:111], v[144:147], v[190:193], v[108:111]
	v_mfma_f32_16x16x32_bf16 v[96:99], v[136:139], v[206:209], v[96:99]
	v_mfma_f32_16x16x32_bf16 v[92:95], v[144:147], v[206:209], v[92:95]
	v_mfma_f32_16x16x32_bf16 v[80:83], v[136:139], v[214:217], v[80:83]
	v_mfma_f32_16x16x32_bf16 v[76:79], v[144:147], v[214:217], v[76:79]
	s_setprio 0
	s_setprio 1
	v_mfma_f32_16x16x32_bf16 v[120:123], v[148:151], v[174:177], v[120:123]
	v_mfma_f32_16x16x32_bf16 v[116:119], v[156:159], v[174:177], v[116:119]
	v_mfma_f32_16x16x32_bf16 v[104:107], v[148:151], v[182:185], v[104:107]
	v_mfma_f32_16x16x32_bf16 v[100:103], v[156:159], v[182:185], v[100:103]
	v_mfma_f32_16x16x32_bf16 v[88:91], v[148:151], v[202:205], v[88:91]
	v_mfma_f32_16x16x32_bf16 v[84:87], v[156:159], v[202:205], v[84:87]
	v_mfma_f32_16x16x32_bf16 v[72:75], v[148:151], v[210:213], v[72:75]
	v_mfma_f32_16x16x32_bf16 v[68:71], v[156:159], v[210:213], v[68:71]
	v_mfma_f32_16x16x32_bf16 v[120:123], v[152:155], v[178:181], v[120:123]
	v_mfma_f32_16x16x32_bf16 v[116:119], v[170:173], v[178:181], v[116:119]
	v_mfma_f32_16x16x32_bf16 v[104:107], v[152:155], v[190:193], v[104:107]
	v_mfma_f32_16x16x32_bf16 v[100:103], v[170:173], v[190:193], v[100:103]
	v_mfma_f32_16x16x32_bf16 v[88:91], v[152:155], v[206:209], v[88:91]
	v_mfma_f32_16x16x32_bf16 v[84:87], v[170:173], v[206:209], v[84:87]
	v_mfma_f32_16x16x32_bf16 v[72:75], v[152:155], v[214:217], v[72:75]
	v_mfma_f32_16x16x32_bf16 v[68:71], v[170:173], v[214:217], v[68:71]
	s_barrier
; #define PG8_STAGE(bufoff, gbase, voff) do { _Pragma("unroll") for (int _i = 0; _i < 2; ++_i) \
;         __builtin_amdgcn_global_load_lds((const unsigned*)((const char*)(gbase) + (voff)[_i]), (PG8_LAS unsigned*)(lds + (bufoff) + ldsw + _i * 8192), 16, 0, 0); } while (0)
; #define PG8_LDA(dst, b, h) do { _Pragma("unroll") for (int m = 0; m < 4; ++m) _Pragma("unroll") for (int k = 0; k < 2; ++k) dst[m][k] = *(const PG8_LAS bf16x8*)(lds + PG8_SA(b, h) + aoff + m * 2048 + k * 1024); } while (0)
; #define PG8_MMA(ai, bj, At, Bt) do { __builtin_amdgcn_s_setprio(1); _Pragma("unroll") for (int m = 0; m < 4; ++m) _Pragma("unroll") for (int n = 0; n < 2; ++n) _Pragma("unroll") for (int k = 0; k < 2; ++k) \
;         acc[ai][bj][m][n] = __builtin_amdgcn_mfma_f32_16x16x32_bf16(Bt[n][k], At[m][k], acc[ai][bj][m][n], 0, 0, 0); __builtin_amdgcn_s_setprio(0); } while (0)
; #define PG8_WAIT_V(n) asm volatile("s_waitcnt vmcnt(" #n ")" ::: "memory")
; #define PG8_WAIT_L(n) asm volatile("s_waitcnt lgkmcnt(" #n ")" ::: "memory")
; #define PG8_BAR __builtin_amdgcn_s_barrier()
; #define PG8_SCHED __builtin_amdgcn_sched_barrier(0)
; template <class Epi, class Sched, bool ALIGN_EPI = false, bool SP2 = false>
; __device__ __forceinline__ void gemm_phase(PG8_LAS unsigned char* lds, const Gemm g, const Sched& S, const Epi& E, const int tid) {
;     ...
;             PG8_LDA(At, 1, 1); PG8_STAGE(PG8_SB(1, 0), b3, voffB); PG8_STAGE(PG8_SB(1, 1), b3 + hstep, voffB); PG8_STAGE(PG8_SA(1, 0), a3, voffA);
;             PG8_WAIT_V(8); PG8_WAIT_L(0); PG8_BAR; PG8_MMA(1, 0, At, B0); PG8_MMA(1, 1, At, B1); PG8_BAR; PG8_SCHED;
	s_setprio 0
	s_add_i32 s18, s86, s2
	v_lshl_add_u64 v[194:195], v[194:195], 0, s[66:67]
	s_mov_b32 m0, s18
	ds_read_b128 v[174:177], v188 offset:49152
	ds_read_b128 v[178:181], v188 offset:50176
	ds_read_b128 v[182:185], v188 offset:51200
	ds_read_b128 v[190:193], v188 offset:52224
	ds_read_b128 v[202:205], v188 offset:53248
	ds_read_b128 v[206:209], v188 offset:54272
	ds_read_b128 v[210:213], v188 offset:55296
	ds_read_b128 v[214:217], v188 offset:56320
	global_load_lds_dwordx4 v[194:195], off
	s_add_i32 m0, s18, 0x2000
	s_add_u32 s18, s34, 0xb0080
	v_lshl_add_u64 v[194:195], v[218:219], 0, s[66:67]
	s_addc_u32 s19, s35, 0
	s_add_i32 s34, s87, s2
	global_load_lds_dwordx4 v[194:195], off
	v_lshl_add_u64 v[194:195], s[18:19], 0, v[160:161]
	s_mov_b32 m0, s34
	s_nop 0
	global_load_lds_dwordx4 v[194:195], off
	v_lshl_add_u64 v[194:195], s[18:19], 0, v[164:165]
	s_add_i32 m0, s34, 0x2000
	s_nop 0
	global_load_lds_dwordx4 v[194:195], off
	v_lshl_add_u64 v[194:195], v[220:221], 0, s[66:67]
	s_mov_b32 m0, s30
	s_nop 0
	global_load_lds_dwordx4 v[194:195], off
	v_lshl_add_u64 v[194:195], v[222:223], 0, s[66:67]
	s_mov_b32 m0, s31
	s_nop 0
	global_load_lds_dwordx4 v[194:195], off
	s_waitcnt vmcnt(8)
	s_waitcnt lgkmcnt(0)
	s_setprio 1
	s_barrier
	v_mfma_f32_16x16x32_bf16 v[64:67], v[124:127], v[174:177], v[64:67]
	v_mfma_f32_16x16x32_bf16 v[60:63], v[140:143], v[174:177], v[60:63]
	v_mfma_f32_16x16x32_bf16 v[48:51], v[124:127], v[182:185], v[48:51]
	v_mfma_f32_16x16x32_bf16 v[44:47], v[140:143], v[182:185], v[44:47]
	v_mfma_f32_16x16x32_bf16 v[32:35], v[124:127], v[202:205], v[32:35]
	v_mfma_f32_16x16x32_bf16 v[28:31], v[140:143], v[202:205], v[28:31]
	v_mfma_f32_16x16x32_bf16 v[16:19], v[124:127], v[210:213], v[16:19]
	v_mfma_f32_16x16x32_bf16 v[12:15], v[140:143], v[210:213], v[12:15]
	v_mfma_f32_16x16x32_bf16 v[64:67], v[136:139], v[178:181], v[64:67]
	v_mfma_f32_16x16x32_bf16 v[60:63], v[144:147], v[178:181], v[60:63]
	v_mfma_f32_16x16x32_bf16 v[48:51], v[136:139], v[190:193], v[48:51]
	v_mfma_f32_16x16x32_bf16 v[44:47], v[144:147], v[190:193], v[44:47]
	v_mfma_f32_16x16x32_bf16 v[32:35], v[136:139], v[206:209], v[32:35]
	v_mfma_f32_16x16x32_bf16 v[28:31], v[144:147], v[206:209], v[28:31]
	v_mfma_f32_16x16x32_bf16 v[16:19], v[136:139], v[214:217], v[16:19]
	v_mfma_f32_16x16x32_bf16 v[12:15], v[144:147], v[214:217], v[12:15]
	s_setprio 0
	s_setprio 1
	v_mfma_f32_16x16x32_bf16 v[56:59], v[148:151], v[174:177], v[56:59]
	v_mfma_f32_16x16x32_bf16 v[52:55], v[156:159], v[174:177], v[52:55]
	v_mfma_f32_16x16x32_bf16 v[40:43], v[148:151], v[182:185], v[40:43]
	v_mfma_f32_16x16x32_bf16 v[36:39], v[156:159], v[182:185], v[36:39]
	v_mfma_f32_16x16x32_bf16 v[24:27], v[148:151], v[202:205], v[24:27]
	v_mfma_f32_16x16x32_bf16 v[20:23], v[156:159], v[202:205], v[20:23]
	v_mfma_f32_16x16x32_bf16 v[8:11], v[148:151], v[210:213], v[8:11]
	v_mfma_f32_16x16x32_bf16 v[4:7], v[156:159], v[210:213], v[4:7]
	v_mfma_f32_16x16x32_bf16 v[56:59], v[152:155], v[178:181], v[56:59]
	v_mfma_f32_16x16x32_bf16 v[52:55], v[170:173], v[178:181], v[52:55]
	v_mfma_f32_16x16x32_bf16 v[40:43], v[152:155], v[190:193], v[40:43]
	v_mfma_f32_16x16x32_bf16 v[36:39], v[170:173], v[190:193], v[36:39]
	v_mfma_f32_16x16x32_bf16 v[24:27], v[152:155], v[206:209], v[24:27]
	v_mfma_f32_16x16x32_bf16 v[20:23], v[170:173], v[206:209], v[20:23]
	v_mfma_f32_16x16x32_bf16 v[8:11], v[152:155], v[214:217], v[8:11]
	v_mfma_f32_16x16x32_bf16 v[4:7], v[170:173], v[214:217], v[4:7]
	s_barrier
	s_setprio 0
	s_add_i32 s85, s85, 2
	s_add_u32 s65, s65, 0x100
	s_addc_u32 s84, s84, 0
	s_cmp_gt_u32 s85, 41
	s_mov_b64 s[18:19], s[42:43]
	s_cbranch_scc0 .LBB0_172
	s_and_b64 vcc, exec, s[54:55]
	s_cbranch_vccz .LBB0_175
	s_barrier

; #define PG8_STAGE(bufoff, gbase, voff) do { _Pragma("unroll") for (int _i = 0; _i < 2; ++_i) \
;         __builtin_amdgcn_global_load_lds((const unsigned*)((const char*)(gbase) + (voff)[_i]), (PG8_LAS unsigned*)(lds + (bufoff) + ldsw + _i * 8192), 16, 0, 0); } while (0)
; #define PG8_LDA(dst, b, h) do { _Pragma("unroll") for (int m = 0; m < 4; ++m) _Pragma("unroll") for (int k = 0; k < 2; ++k) dst[m][k] = *(const PG8_LAS bf16x8*)(lds + PG8_SA(b, h) + aoff + m * 2048 + k * 1024); } while (0)
; #define PG8_LDB(dst, b, h) do { _Pragma("unroll") for (int n = 0; n < 2; ++n) _Pragma("unroll") for (int k = 0; k < 2; ++k) dst[n][k] = *(const PG8_LAS bf16x8*)(lds + PG8_SB(b, h) + boff + n * 2048 + k * 1024); } while (0)
; #define PG8_MMA(ai, bj, At, Bt) do { __builtin_amdgcn_s_setprio(1); _Pragma("unroll") for (int m = 0; m < 4; ++m) _Pragma("unroll") for (int n = 0; n < 2; ++n) _Pragma("unroll") for (int k = 0; k < 2; ++k) \
;         acc[ai][bj][m][n] = __builtin_amdgcn_mfma_f32_16x16x32_bf16(Bt[n][k], At[m][k], acc[ai][bj][m][n], 0, 0, 0); __builtin_amdgcn_s_setprio(0); } while (0)
; #define PG8_WAIT_V(n) asm volatile("s_waitcnt vmcnt(" #n ")" ::: "memory")
; #define PG8_WAIT_L(n) asm volatile("s_waitcnt lgkmcnt(" #n ")" ::: "memory")
; template <class Epi, class Sched, bool ALIGN_EPI = false, bool SP2 = false>
; __device__ __forceinline__ void gemm_phase(PG8_LAS unsigned char* lds, const Gemm g, const Sched& S, const Epi& E, const int tid) {
;     ...
;             const bool last = (t == nt - 2);
;             const char* a1 = cA + (size_t)(t + 1) * kstep;
;             const char* a2 = last ? nA : cA + (size_t)(t + 2) * kstep; const char* b2 = last ? nB : cB + (size_t)(t + 2) * kstep;
;             const char* a3 = a2 + kstep; const char* b3 = b2 + kstep;
;             if (last && has_next) S.a_ready(nxt);
;             if constexpr (Epi::MID) { if (t == nt / 2) { PG8_SCHED; E.mid(acc, cur, wr, wc, fr, fq); PG8_SCHED; } }
;             if constexpr (SP2) {
;             PG8_LDB(B0, 0, 0); PG8_LDB(B1, 0, 1); PG8_SCHED; PG8_LDA(At, 0, 0); PG8_STAGE(PG8_SA(1, 1), a1 + hstep, voffA);
;             PG8_WAIT_V(8); PG8_WAIT_L(0); PG8_BAR; PG8_MMA(0, 0, At, B0); PG8_MMA(0, 1, At, B1); PG8_BAR; PG8_SCHED;
;             PG8_LDA(At, 0, 1); PG8_STAGE(PG8_SB(0, 0), b2, voffB); PG8_STAGE(PG8_SB(0, 1), b2 + hstep, voffB); PG8_STAGE(PG8_SA(0, 0), a2, voffA);
.LBB0_302:
	s_add_u32 s34, s18, 0xfffc0080
	s_addc_u32 s35, s19, -1
	s_add_i32 s84, 0, 0x10000
	s_cmp_eq_u32 s57, 12
	s_cselect_b32 s47, s22, s35
	s_cselect_b32 s46, s30, s34
	s_cselect_b32 s35, s31, s55
	s_cselect_b32 s34, s43, s45
	s_add_i32 s86, 0, 0x14000
	v_add_u32_e32 v154, s84, v160
	v_add_u32_e32 v158, s86, v160
	ds_read_b128 v[142:145], v154
	ds_read_b128 v[146:149], v154 offset:1024
	ds_read_b128 v[150:153], v154 offset:2048
	ds_read_b128 v[154:157], v154 offset:3072
	ds_read_b128 v[164:167], v158
	ds_read_b128 v[168:171], v158 offset:1024
	ds_read_b128 v[172:175], v158 offset:2048
	ds_read_b128 v[176:179], v158 offset:3072
	v_lshl_add_u64 v[158:159], s[18:19], 0, v[138:139]
	s_add_i32 m0, s62, 0xc000
	ds_read_b128 v[180:183], v163
	ds_read_b128 v[184:187], v163 offset:1024
	ds_read_b128 v[188:191], v163 offset:2048
	ds_read_b128 v[192:195], v163 offset:3072
	ds_read_b128 v[202:205], v163 offset:4096
	ds_read_b128 v[206:209], v163 offset:5120
	ds_read_b128 v[210:213], v163 offset:6144
	ds_read_b128 v[214:217], v163 offset:7168
	global_load_lds_dwordx4 v[158:159], off
	v_lshl_add_u64 v[158:159], s[18:19], 0, v[140:141]
	s_add_i32 m0, s62, 0xe000
	s_nop 0
	global_load_lds_dwordx4 v[158:159], off
	s_waitcnt vmcnt(8)
	s_waitcnt lgkmcnt(0)
	s_setprio 1
	s_barrier
	v_mfma_f32_16x16x32_bf16 v[128:131], v[142:145], v[180:183], v[128:131]
	v_mfma_f32_16x16x32_bf16 v[124:127], v[150:153], v[180:183], v[124:127]
	v_mfma_f32_16x16x32_bf16 v[112:115], v[142:145], v[188:191], v[112:115]
	v_mfma_f32_16x16x32_bf16 v[108:111], v[150:153], v[188:191], v[108:111]
	v_mfma_f32_16x16x32_bf16 v[96:99], v[142:145], v[202:205], v[96:99]
	v_mfma_f32_16x16x32_bf16 v[92:95], v[150:153], v[202:205], v[92:95]
	v_mfma_f32_16x16x32_bf16 v[80:83], v[142:145], v[210:213], v[80:83]
	v_mfma_f32_16x16x32_bf16 v[76:79], v[150:153], v[210:213], v[76:79]
	v_mfma_f32_16x16x32_bf16 v[128:131], v[146:149], v[184:187], v[128:131]
	v_mfma_f32_16x16x32_bf16 v[124:127], v[154:157], v[184:187], v[124:127]
	v_mfma_f32_16x16x32_bf16 v[112:115], v[146:149], v[192:195], v[112:115]
	v_mfma_f32_16x16x32_bf16 v[108:111], v[154:157], v[192:195], v[108:111]
	v_mfma_f32_16x16x32_bf16 v[96:99], v[146:149], v[206:209], v[96:99]
	v_mfma_f32_16x16x32_bf16 v[92:95], v[154:157], v[206:209], v[92:95]
	v_mfma_f32_16x16x32_bf16 v[80:83], v[146:149], v[214:217], v[80:83]
	v_mfma_f32_16x16x32_bf16 v[76:79], v[154:157], v[214:217], v[76:79]
	s_setprio 0
	s_setprio 1
	v_mfma_f32_16x16x32_bf16 v[120:123], v[164:167], v[180:183], v[120:123]
	v_mfma_f32_16x16x32_bf16 v[116:119], v[172:175], v[180:183], v[116:119]
	v_mfma_f32_16x16x32_bf16 v[104:107], v[164:167], v[188:191], v[104:107]
	v_mfma_f32_16x16x32_bf16 v[100:103], v[172:175], v[188:191], v[100:103]
	v_mfma_f32_16x16x32_bf16 v[88:91], v[164:167], v[202:205], v[88:91]
	v_mfma_f32_16x16x32_bf16 v[84:87], v[172:175], v[202:205], v[84:87]
	v_mfma_f32_16x16x32_bf16 v[72:75], v[164:167], v[210:213], v[72:75]
	v_mfma_f32_16x16x32_bf16 v[68:71], v[172:175], v[210:213], v[68:71]
	v_mfma_f32_16x16x32_bf16 v[120:123], v[168:171], v[184:187], v[120:123]
	v_mfma_f32_16x16x32_bf16 v[116:119], v[176:179], v[184:187], v[116:119]
	v_mfma_f32_16x16x32_bf16 v[104:107], v[168:171], v[192:195], v[104:107]
	v_mfma_f32_16x16x32_bf16 v[100:103], v[176:179], v[192:195], v[100:103]
	v_mfma_f32_16x16x32_bf16 v[88:91], v[168:171], v[206:209], v[88:91]
	v_mfma_f32_16x16x32_bf16 v[84:87], v[176:179], v[206:209], v[84:87]
	v_mfma_f32_16x16x32_bf16 v[72:75], v[168:171], v[214:217], v[72:75]
	v_mfma_f32_16x16x32_bf16 v[68:71], v[176:179], v[214:217], v[68:71]
	s_barrier
	s_setprio 0
	s_add_i32 s84, s84, s3
	v_lshl_add_u64 v[158:159], s[34:35], 0, v[132:133]
	s_mov_b32 m0, s84
	ds_read_b128 v[180:183], v163 offset:16384
	ds_read_b128 v[184:187], v163 offset:17408
	ds_read_b128 v[188:191], v163 offset:18432
	ds_read_b128 v[192:195], v163 offset:19456
	ds_read_b128 v[202:205], v163 offset:20480
	ds_read_b128 v[206:209], v163 offset:21504
	ds_read_b128 v[210:213], v163 offset:22528
	ds_read_b128 v[214:217], v163 offset:23552
	global_load_lds_dwordx4 v[158:159], off
	s_add_i32 m0, s84, 0x2000
	s_add_u32 s84, s34, 0x40000
	v_lshl_add_u64 v[218:219], s[34:35], 0, v[136:137]
	s_addc_u32 s85, s35, 0
	s_add_i32 s86, s86, s3
	global_load_lds_dwordx4 v[218:219], off
	v_lshl_add_u64 v[220:221], s[84:85], 0, v[132:133]
	s_mov_b32 m0, s86
	v_lshl_add_u64 v[222:223], s[46:47], 0, v[134:135]
	global_load_lds_dwordx4 v[220:221], off
	v_lshl_add_u64 v[220:221], s[84:85], 0, v[136:137]
	s_add_i32 m0, s86, 0x2000
	s_nop 0
	global_load_lds_dwordx4 v[220:221], off
	v_lshl_add_u64 v[220:221], s[46:47], 0, v[0:1]
	s_mov_b32 m0, s62
	s_nop 0
	global_load_lds_dwordx4 v[220:221], off
	s_mov_b32 m0, s63
	s_nop 0
	global_load_lds_dwordx4 v[222:223], off
	s_waitcnt vmcnt(8)
	s_waitcnt lgkmcnt(0)
	s_setprio 1
	s_barrier
; #define PG8_STAGE(bufoff, gbase, voff) do { _Pragma("unroll") for (int _i = 0; _i < 2; ++_i) \
;         __builtin_amdgcn_global_load_lds((const unsigned*)((const char*)(gbase) + (voff)[_i]), (PG8_LAS unsigned*)(lds + (bufoff) + ldsw + _i * 8192), 16, 0, 0); } while (0)
; #define PG8_LDA(dst, b, h) do { _Pragma("unroll") for (int m = 0; m < 4; ++m) _Pragma("unroll") for (int k = 0; k < 2; ++k) dst[m][k] = *(const PG8_LAS bf16x8*)(lds + PG8_SA(b, h) + aoff + m * 2048 + k * 1024); } while (0)
; #define PG8_LDB(dst, b, h) do { _Pragma("unroll") for (int n = 0; n < 2; ++n) _Pragma("unroll") for (int k = 0; k < 2; ++k) dst[n][k] = *(const PG8_LAS bf16x8*)(lds + PG8_SB(b, h) + boff + n * 2048 + k * 1024); } while (0)
; #define PG8_MMA(ai, bj, At, Bt) do { __builtin_amdgcn_s_setprio(1); _Pragma("unroll") for (int m = 0; m < 4; ++m) _Pragma("unroll") for (int n = 0; n < 2; ++n) _Pragma("unroll") for (int k = 0; k < 2; ++k) \
;         acc[ai][bj][m][n] = __builtin_amdgcn_mfma_f32_16x16x32_bf16(Bt[n][k], At[m][k], acc[ai][bj][m][n], 0, 0, 0); __builtin_amdgcn_s_setprio(0); } while (0)
; #define PG8_WAIT_V(n) asm volatile("s_waitcnt vmcnt(" #n ")" ::: "memory")
; #define PG8_WAIT_L(n) asm volatile("s_waitcnt lgkmcnt(" #n ")" ::: "memory")
; #define PG8_BAR __builtin_amdgcn_s_barrier()
; #define PG8_SCHED __builtin_amdgcn_sched_barrier(0)
; template <class Epi, class Sched, bool ALIGN_EPI = false, bool SP2 = false>
; __device__ __forceinline__ void gemm_phase(PG8_LAS unsigned char* lds, const Gemm g, const Sched& S, const Epi& E, const int tid) {
;     ...
;             PG8_WAIT_V(8); PG8_WAIT_L(0); PG8_BAR; PG8_MMA(1, 0, At, B0); PG8_MMA(1, 1, At, B1); PG8_BAR; PG8_SCHED;
;             PG8_LDB(B0, 1, 0); PG8_LDB(B1, 1, 1); PG8_SCHED; PG8_LDA(At, 1, 0); PG8_STAGE(PG8_SA(0, 1), a2 + hstep, voffA);
;             PG8_WAIT_V(8); PG8_WAIT_L(0); PG8_BAR; PG8_MMA(0, 0, At, B0); PG8_MMA(0, 1, At, B1); PG8_BAR; PG8_SCHED;
	v_mfma_f32_16x16x32_bf16 v[64:67], v[142:145], v[180:183], v[64:67]
	v_mfma_f32_16x16x32_bf16 v[60:63], v[150:153], v[180:183], v[60:63]
	v_mfma_f32_16x16x32_bf16 v[48:51], v[142:145], v[188:191], v[48:51]
	v_mfma_f32_16x16x32_bf16 v[44:47], v[150:153], v[188:191], v[44:47]
	v_mfma_f32_16x16x32_bf16 v[32:35], v[142:145], v[202:205], v[32:35]
	v_mfma_f32_16x16x32_bf16 v[28:31], v[150:153], v[202:205], v[28:31]
	v_mfma_f32_16x16x32_bf16 v[16:19], v[142:145], v[210:213], v[16:19]
	v_mfma_f32_16x16x32_bf16 v[12:15], v[150:153], v[210:213], v[12:15]
	v_mfma_f32_16x16x32_bf16 v[64:67], v[146:149], v[184:187], v[64:67]
	v_mfma_f32_16x16x32_bf16 v[60:63], v[154:157], v[184:187], v[60:63]
	v_mfma_f32_16x16x32_bf16 v[48:51], v[146:149], v[192:195], v[48:51]
	v_mfma_f32_16x16x32_bf16 v[44:47], v[154:157], v[192:195], v[44:47]
	v_mfma_f32_16x16x32_bf16 v[32:35], v[146:149], v[206:209], v[32:35]
	v_mfma_f32_16x16x32_bf16 v[28:31], v[154:157], v[206:209], v[28:31]
	v_mfma_f32_16x16x32_bf16 v[16:19], v[146:149], v[214:217], v[16:19]
	v_mfma_f32_16x16x32_bf16 v[12:15], v[154:157], v[214:217], v[12:15]
	s_setprio 0
	s_setprio 1
	v_mfma_f32_16x16x32_bf16 v[56:59], v[164:167], v[180:183], v[56:59]
	v_mfma_f32_16x16x32_bf16 v[52:55], v[172:175], v[180:183], v[52:55]
	v_mfma_f32_16x16x32_bf16 v[40:43], v[164:167], v[188:191], v[40:43]
	v_mfma_f32_16x16x32_bf16 v[36:39], v[172:175], v[188:191], v[36:39]
	v_mfma_f32_16x16x32_bf16 v[24:27], v[164:167], v[202:205], v[24:27]
	v_mfma_f32_16x16x32_bf16 v[20:23], v[172:175], v[202:205], v[20:23]
	v_mfma_f32_16x16x32_bf16 v[8:11], v[164:167], v[210:213], v[8:11]
	v_mfma_f32_16x16x32_bf16 v[4:7], v[172:175], v[210:213], v[4:7]
	v_mfma_f32_16x16x32_bf16 v[56:59], v[168:171], v[184:187], v[56:59]
	v_mfma_f32_16x16x32_bf16 v[52:55], v[176:179], v[184:187], v[52:55]
	v_mfma_f32_16x16x32_bf16 v[40:43], v[168:171], v[192:195], v[40:43]
	v_mfma_f32_16x16x32_bf16 v[36:39], v[176:179], v[192:195], v[36:39]
	v_mfma_f32_16x16x32_bf16 v[24:27], v[168:171], v[206:209], v[24:27]
	v_mfma_f32_16x16x32_bf16 v[20:23], v[176:179], v[206:209], v[20:23]
	v_mfma_f32_16x16x32_bf16 v[8:11], v[168:171], v[214:217], v[8:11]
	v_mfma_f32_16x16x32_bf16 v[4:7], v[176:179], v[214:217], v[4:7]
	s_barrier
	s_setprio 0
	s_add_i32 s84, 0, 0x18000
	s_add_i32 s85, 0, 0x1c000
	v_add_u32_e32 v154, s84, v160
	v_add_u32_e32 v176, s85, v160
	ds_read_b128 v[142:145], v154
	ds_read_b128 v[146:149], v154 offset:1024
	ds_read_b128 v[150:153], v154 offset:2048
	ds_read_b128 v[154:157], v154 offset:3072
	ds_read_b128 v[164:167], v176
	ds_read_b128 v[168:171], v176 offset:1024
	ds_read_b128 v[172:175], v176 offset:2048
	ds_read_b128 v[176:179], v176 offset:3072
	s_add_u32 s46, s46, 0x40000
	s_addc_u32 s47, s47, 0
	s_mov_b32 m0, s64
	v_lshl_add_u64 v[224:225], s[46:47], 0, v[0:1]
	ds_read_b128 v[180:183], v163 offset:32768
	ds_read_b128 v[184:187], v163 offset:33792
	ds_read_b128 v[188:191], v163 offset:34816
	ds_read_b128 v[192:195], v163 offset:35840
	ds_read_b128 v[202:205], v163 offset:36864
	ds_read_b128 v[206:209], v163 offset:37888
	ds_read_b128 v[210:213], v163 offset:38912
	ds_read_b128 v[214:217], v163 offset:39936
	global_load_lds_dwordx4 v[224:225], off
	v_lshl_add_u64 v[224:225], s[46:47], 0, v[134:135]
	s_mov_b32 m0, s65
	s_nop 0
	global_load_lds_dwordx4 v[224:225], off
	s_waitcnt vmcnt(8)
	s_waitcnt lgkmcnt(0)
	s_setprio 1
	s_barrier
	v_mfma_f32_16x16x32_bf16 v[128:131], v[142:145], v[180:183], v[128:131]
	v_mfma_f32_16x16x32_bf16 v[124:127], v[150:153], v[180:183], v[124:127]
	v_mfma_f32_16x16x32_bf16 v[112:115], v[142:145], v[188:191], v[112:115]
	v_mfma_f32_16x16x32_bf16 v[108:111], v[150:153], v[188:191], v[108:111]
	v_mfma_f32_16x16x32_bf16 v[96:99], v[142:145], v[202:205], v[96:99]
	v_mfma_f32_16x16x32_bf16 v[92:95], v[150:153], v[202:205], v[92:95]
	v_mfma_f32_16x16x32_bf16 v[80:83], v[142:145], v[210:213], v[80:83]
	v_mfma_f32_16x16x32_bf16 v[76:79], v[150:153], v[210:213], v[76:79]
	v_mfma_f32_16x16x32_bf16 v[128:131], v[146:149], v[184:187], v[128:131]
	v_mfma_f32_16x16x32_bf16 v[124:127], v[154:157], v[184:187], v[124:127]
	v_mfma_f32_16x16x32_bf16 v[112:115], v[146:149], v[192:195], v[112:115]
	v_mfma_f32_16x16x32_bf16 v[108:111], v[154:157], v[192:195], v[108:111]
	v_mfma_f32_16x16x32_bf16 v[96:99], v[146:149], v[206:209], v[96:99]
	v_mfma_f32_16x16x32_bf16 v[92:95], v[154:157], v[206:209], v[92:95]
	v_mfma_f32_16x16x32_bf16 v[80:83], v[146:149], v[214:217], v[80:83]
	v_mfma_f32_16x16x32_bf16 v[76:79], v[154:157], v[214:217], v[76:79]
	s_setprio 0
	s_setprio 1
	v_mfma_f32_16x16x32_bf16 v[120:123], v[164:167], v[180:183], v[120:123]
	v_mfma_f32_16x16x32_bf16 v[116:119], v[172:175], v[180:183], v[116:119]
	v_mfma_f32_16x16x32_bf16 v[104:107], v[164:167], v[188:191], v[104:107]
	v_mfma_f32_16x16x32_bf16 v[100:103], v[172:175], v[188:191], v[100:103]
	v_mfma_f32_16x16x32_bf16 v[88:91], v[164:167], v[202:205], v[88:91]
	v_mfma_f32_16x16x32_bf16 v[84:87], v[172:175], v[202:205], v[84:87]
	v_mfma_f32_16x16x32_bf16 v[72:75], v[164:167], v[210:213], v[72:75]
	v_mfma_f32_16x16x32_bf16 v[68:71], v[172:175], v[210:213], v[68:71]
	v_mfma_f32_16x16x32_bf16 v[120:123], v[168:171], v[184:187], v[120:123]
	v_mfma_f32_16x16x32_bf16 v[116:119], v[176:179], v[184:187], v[116:119]
	v_mfma_f32_16x16x32_bf16 v[104:107], v[168:171], v[192:195], v[104:107]
	v_mfma_f32_16x16x32_bf16 v[100:103], v[176:179], v[192:195], v[100:103]
	v_mfma_f32_16x16x32_bf16 v[88:91], v[168:171], v[206:209], v[88:91]
	v_mfma_f32_16x16x32_bf16 v[84:87], v[176:179], v[206:209], v[84:87]
	v_mfma_f32_16x16x32_bf16 v[72:75], v[168:171], v[214:217], v[72:75]
	v_mfma_f32_16x16x32_bf16 v[68:71], v[176:179], v[214:217], v[68:71]
	s_barrier
; #define PG8_STAGE(bufoff, gbase, voff) do { _Pragma("unroll") for (int _i = 0; _i < 2; ++_i) \
;         __builtin_amdgcn_global_load_lds((const unsigned*)((const char*)(gbase) + (voff)[_i]), (PG8_LAS unsigned*)(lds + (bufoff) + ldsw + _i * 8192), 16, 0, 0); } while (0)
; #define PG8_LDA(dst, b, h) do { _Pragma("unroll") for (int m = 0; m < 4; ++m) _Pragma("unroll") for (int k = 0; k < 2; ++k) dst[m][k] = *(const PG8_LAS bf16x8*)(lds + PG8_SA(b, h) + aoff + m * 2048 + k * 1024); } while (0)
; #define PG8_MMA(ai, bj, At, Bt) do { __builtin_amdgcn_s_setprio(1); _Pragma("unroll") for (int m = 0; m < 4; ++m) _Pragma("unroll") for (int n = 0; n < 2; ++n) _Pragma("unroll") for (int k = 0; k < 2; ++k) \
;         acc[ai][bj][m][n] = __builtin_amdgcn_mfma_f32_16x16x32_bf16(Bt[n][k], At[m][k], acc[ai][bj][m][n], 0, 0, 0); __builtin_amdgcn_s_setprio(0); } while (0)
; #define PG8_WAIT_V(n) asm volatile("s_waitcnt vmcnt(" #n ")" ::: "memory")
; #define PG8_WAIT_L(n) asm volatile("s_waitcnt lgkmcnt(" #n ")" ::: "memory")
; #define PG8_BAR __builtin_amdgcn_s_barrier()
; #define PG8_SCHED __builtin_amdgcn_sched_barrier(0)
; template <class Epi, class Sched, bool ALIGN_EPI = false, bool SP2 = false>
; __device__ __forceinline__ void gemm_phase(PG8_LAS unsigned char* lds, const Gemm g, const Sched& S, const Epi& E, const int tid) {
;     ...
;             PG8_LDA(At, 1, 1); PG8_STAGE(PG8_SB(1, 0), b3, voffB); PG8_STAGE(PG8_SB(1, 1), b3 + hstep, voffB); PG8_STAGE(PG8_SA(1, 0), a3, voffA);
;             PG8_WAIT_V(8); PG8_WAIT_L(0); PG8_BAR; PG8_MMA(1, 0, At, B0); PG8_MMA(1, 1, At, B1); PG8_BAR; PG8_SCHED;
	s_setprio 0
	s_add_i32 s46, s84, s3
	v_lshl_add_u64 v[158:159], v[158:159], 0, s[66:67]
	s_mov_b32 m0, s46
	ds_read_b128 v[180:183], v163 offset:49152
	ds_read_b128 v[184:187], v163 offset:50176
	ds_read_b128 v[188:191], v163 offset:51200
	ds_read_b128 v[192:195], v163 offset:52224
	ds_read_b128 v[202:205], v163 offset:53248
	ds_read_b128 v[206:209], v163 offset:54272
	ds_read_b128 v[210:213], v163 offset:55296
	ds_read_b128 v[214:217], v163 offset:56320
	global_load_lds_dwordx4 v[158:159], off
	s_add_i32 m0, s46, 0x2000
	s_add_u32 s34, s34, 0x40080
	v_lshl_add_u64 v[158:159], v[218:219], 0, s[66:67]
	s_addc_u32 s35, s35, 0
	s_add_i32 s46, s85, s3
	global_load_lds_dwordx4 v[158:159], off
	v_lshl_add_u64 v[158:159], s[34:35], 0, v[132:133]
	s_mov_b32 m0, s46
	s_nop 0
	global_load_lds_dwordx4 v[158:159], off
	v_lshl_add_u64 v[158:159], s[34:35], 0, v[136:137]
	s_add_i32 m0, s46, 0x2000
	s_nop 0
	global_load_lds_dwordx4 v[158:159], off
	v_lshl_add_u64 v[158:159], v[220:221], 0, s[66:67]
	s_mov_b32 m0, s23
	s_nop 0
	global_load_lds_dwordx4 v[158:159], off
	v_lshl_add_u64 v[158:159], v[222:223], 0, s[66:67]
	s_mov_b32 m0, s28
	s_nop 0
	global_load_lds_dwordx4 v[158:159], off
	s_waitcnt vmcnt(8)
	s_waitcnt lgkmcnt(0)
	s_setprio 1
	s_barrier
	v_mfma_f32_16x16x32_bf16 v[64:67], v[142:145], v[180:183], v[64:67]
	v_mfma_f32_16x16x32_bf16 v[60:63], v[150:153], v[180:183], v[60:63]
	v_mfma_f32_16x16x32_bf16 v[48:51], v[142:145], v[188:191], v[48:51]
	v_mfma_f32_16x16x32_bf16 v[44:47], v[150:153], v[188:191], v[44:47]
	v_mfma_f32_16x16x32_bf16 v[32:35], v[142:145], v[202:205], v[32:35]
	v_mfma_f32_16x16x32_bf16 v[28:31], v[150:153], v[202:205], v[28:31]
	v_mfma_f32_16x16x32_bf16 v[16:19], v[142:145], v[210:213], v[16:19]
	v_mfma_f32_16x16x32_bf16 v[12:15], v[150:153], v[210:213], v[12:15]
	v_mfma_f32_16x16x32_bf16 v[64:67], v[146:149], v[184:187], v[64:67]
	v_mfma_f32_16x16x32_bf16 v[60:63], v[154:157], v[184:187], v[60:63]
	v_mfma_f32_16x16x32_bf16 v[48:51], v[146:149], v[192:195], v[48:51]
	v_mfma_f32_16x16x32_bf16 v[44:47], v[154:157], v[192:195], v[44:47]
	v_mfma_f32_16x16x32_bf16 v[32:35], v[146:149], v[206:209], v[32:35]
	v_mfma_f32_16x16x32_bf16 v[28:31], v[154:157], v[206:209], v[28:31]
	v_mfma_f32_16x16x32_bf16 v[16:19], v[146:149], v[214:217], v[16:19]
	v_mfma_f32_16x16x32_bf16 v[12:15], v[154:157], v[214:217], v[12:15]
	s_setprio 0
	s_setprio 1
	v_mfma_f32_16x16x32_bf16 v[56:59], v[164:167], v[180:183], v[56:59]
	v_mfma_f32_16x16x32_bf16 v[52:55], v[172:175], v[180:183], v[52:55]
	v_mfma_f32_16x16x32_bf16 v[40:43], v[164:167], v[188:191], v[40:43]
	v_mfma_f32_16x16x32_bf16 v[36:39], v[172:175], v[188:191], v[36:39]
	v_mfma_f32_16x16x32_bf16 v[24:27], v[164:167], v[202:205], v[24:27]
	v_mfma_f32_16x16x32_bf16 v[20:23], v[172:175], v[202:205], v[20:23]
	v_mfma_f32_16x16x32_bf16 v[8:11], v[164:167], v[210:213], v[8:11]
	v_mfma_f32_16x16x32_bf16 v[4:7], v[172:175], v[210:213], v[4:7]
	v_mfma_f32_16x16x32_bf16 v[56:59], v[168:171], v[184:187], v[56:59]
	v_mfma_f32_16x16x32_bf16 v[52:55], v[176:179], v[184:187], v[52:55]
	v_mfma_f32_16x16x32_bf16 v[40:43], v[168:171], v[192:195], v[40:43]
	v_mfma_f32_16x16x32_bf16 v[36:39], v[176:179], v[192:195], v[36:39]
	v_mfma_f32_16x16x32_bf16 v[24:27], v[168:171], v[206:209], v[24:27]
	v_mfma_f32_16x16x32_bf16 v[20:23], v[176:179], v[206:209], v[20:23]
	v_mfma_f32_16x16x32_bf16 v[8:11], v[168:171], v[214:217], v[8:11]
	v_mfma_f32_16x16x32_bf16 v[4:7], v[176:179], v[214:217], v[4:7]
	s_barrier
	s_setprio 0
	s_add_i32 s57, s57, 2
	s_add_u32 s18, s18, 0x100
	s_addc_u32 s19, s19, 0
	s_add_u32 s45, s45, 0x100
	s_addc_u32 s55, s55, 0
	s_cmp_gt_u32 s57, 13
	s_cbranch_scc0 .LBB0_302
	s_and_b64 vcc, exec, s[52:53]
	s_cbranch_vccz .LBB0_305
	s_barrier
